# loop-edge edit (asm guide 7.11): K-loop counter/pointer bookkeeping and exit test moved in front of the loop-closing barrier in all 13 GEMM K-loops
# baseline (speedup 1.0000x reference)
.LBB0_225:
	ds_read_b128 v[146:149], v155
	ds_read_b128 v[150:153], v155 offset:1024
	ds_read_b128 v[158:161], v155 offset:2048
	ds_read_b128 v[162:165], v155 offset:3072
	ds_read_b128 v[166:169], v156
	ds_read_b128 v[170:173], v156 offset:1024
	ds_read_b128 v[174:177], v156 offset:2048
	ds_read_b128 v[182:185], v156 offset:3072
	s_add_u32 s50, s48, 0xfffc0080
	s_addc_u32 s51, s49, -1
	s_cmp_eq_u32 s71, 12
	s_cselect_b32 s53, s7, s51
	s_cselect_b32 s52, s9, s50
	s_cselect_b32 s51, s37, s70
	s_cselect_b32 s50, s39, s69
	v_lshl_add_u64 v[178:179], s[48:49], 0, v[138:139]
	s_add_i32 m0, s56, 0xc000
	ds_read_b128 v[186:189], v157
	ds_read_b128 v[190:193], v157 offset:1024
	ds_read_b128 v[194:197], v157 offset:2048
	ds_read_b128 v[198:201], v157 offset:3072
	ds_read_b128 v[202:205], v157 offset:4096
	ds_read_b128 v[206:209], v157 offset:5120
	ds_read_b128 v[210:213], v157 offset:6144
	ds_read_b128 v[214:217], v157 offset:7168
	global_load_lds_dwordx4 v[178:179], off
	v_lshl_add_u64 v[178:179], s[48:49], 0, v[140:141]
	s_add_i32 m0, s56, 0xe000
	s_nop 0
	global_load_lds_dwordx4 v[178:179], off
	s_waitcnt vmcnt(8)
	s_waitcnt lgkmcnt(0)
	s_barrier
	s_setprio 1
	s_waitcnt lgkmcnt(0)
	v_mfma_f32_16x16x32_bf16 v[124:127], v[146:149], v[186:189], v[124:127]
	v_mfma_f32_16x16x32_bf16 v[120:123], v[158:161], v[186:189], v[120:123]
	v_mfma_f32_16x16x32_bf16 v[108:111], v[146:149], v[194:197], v[108:111]
	v_mfma_f32_16x16x32_bf16 v[104:107], v[158:161], v[194:197], v[104:107]
	v_mfma_f32_16x16x32_bf16 v[92:95], v[146:149], v[202:205], v[92:95]
	v_mfma_f32_16x16x32_bf16 v[88:91], v[158:161], v[202:205], v[88:91]
	v_mfma_f32_16x16x32_bf16 v[76:79], v[146:149], v[210:213], v[76:79]
	v_mfma_f32_16x16x32_bf16 v[72:75], v[158:161], v[210:213], v[72:75]
	v_mfma_f32_16x16x32_bf16 v[124:127], v[150:153], v[190:193], v[124:127]
	v_mfma_f32_16x16x32_bf16 v[120:123], v[162:165], v[190:193], v[120:123]
	v_mfma_f32_16x16x32_bf16 v[108:111], v[150:153], v[198:201], v[108:111]
	v_mfma_f32_16x16x32_bf16 v[104:107], v[162:165], v[198:201], v[104:107]
	v_mfma_f32_16x16x32_bf16 v[92:95], v[150:153], v[206:209], v[92:95]
	v_mfma_f32_16x16x32_bf16 v[88:91], v[162:165], v[206:209], v[88:91]
	v_mfma_f32_16x16x32_bf16 v[76:79], v[150:153], v[214:217], v[76:79]
	v_mfma_f32_16x16x32_bf16 v[72:75], v[162:165], v[214:217], v[72:75]
	s_setprio 0
	s_setprio 1
	v_mfma_f32_16x16x32_bf16 v[116:119], v[166:169], v[186:189], v[116:119]
	v_mfma_f32_16x16x32_bf16 v[112:115], v[174:177], v[186:189], v[112:115]
	v_mfma_f32_16x16x32_bf16 v[100:103], v[166:169], v[194:197], v[100:103]
	v_mfma_f32_16x16x32_bf16 v[96:99], v[174:177], v[194:197], v[96:99]
	v_mfma_f32_16x16x32_bf16 v[84:87], v[166:169], v[202:205], v[84:87]
	v_mfma_f32_16x16x32_bf16 v[80:83], v[174:177], v[202:205], v[80:83]
	v_mfma_f32_16x16x32_bf16 v[68:71], v[166:169], v[210:213], v[68:71]
	v_mfma_f32_16x16x32_bf16 v[64:67], v[174:177], v[210:213], v[64:67]
	v_mfma_f32_16x16x32_bf16 v[116:119], v[170:173], v[190:193], v[116:119]
	v_mfma_f32_16x16x32_bf16 v[112:115], v[182:185], v[190:193], v[112:115]
	v_mfma_f32_16x16x32_bf16 v[100:103], v[170:173], v[198:201], v[100:103]
	v_mfma_f32_16x16x32_bf16 v[96:99], v[182:185], v[198:201], v[96:99]
	v_mfma_f32_16x16x32_bf16 v[84:87], v[170:173], v[206:209], v[84:87]
	v_mfma_f32_16x16x32_bf16 v[80:83], v[182:185], v[206:209], v[80:83]
	v_mfma_f32_16x16x32_bf16 v[68:71], v[170:173], v[214:217], v[68:71]
	v_mfma_f32_16x16x32_bf16 v[64:67], v[182:185], v[214:217], v[64:67]
	s_setprio 0
	s_barrier
	s_add_i32 s72, s64, s55
	v_lshl_add_u64 v[178:179], s[50:51], 0, v[130:131]
	s_mov_b32 m0, s72
	ds_read_b128 v[186:189], v157 offset:16384
	ds_read_b128 v[190:193], v157 offset:17408
	ds_read_b128 v[194:197], v157 offset:18432
	ds_read_b128 v[198:201], v157 offset:19456
	ds_read_b128 v[202:205], v157 offset:20480
	ds_read_b128 v[206:209], v157 offset:21504
	ds_read_b128 v[210:213], v157 offset:22528
	ds_read_b128 v[214:217], v157 offset:23552
	global_load_lds_dwordx4 v[178:179], off
	s_add_i32 m0, s72, 0x2000
	s_add_u32 s72, s50, 0x40000
	v_lshl_add_u64 v[218:219], s[50:51], 0, v[134:135]
	s_addc_u32 s73, s51, 0
	s_add_i32 s74, s65, s55
	global_load_lds_dwordx4 v[218:219], off
	v_lshl_add_u64 v[220:221], s[72:73], 0, v[130:131]
	s_mov_b32 m0, s74
	v_lshl_add_u64 v[222:223], s[52:53], 0, v[132:133]
	global_load_lds_dwordx4 v[220:221], off
	v_lshl_add_u64 v[220:221], s[72:73], 0, v[134:135]
	s_add_i32 m0, s74, 0x2000
	s_nop 0
	global_load_lds_dwordx4 v[220:221], off
	v_lshl_add_u64 v[220:221], s[52:53], 0, v[128:129]
	s_mov_b32 m0, s56
	s_nop 0
	global_load_lds_dwordx4 v[220:221], off
	s_mov_b32 m0, s57
	s_nop 0
	global_load_lds_dwordx4 v[222:223], off
	s_waitcnt vmcnt(8)
	s_waitcnt lgkmcnt(0)
	s_barrier
	s_setprio 1
	s_waitcnt lgkmcnt(0)
	v_mfma_f32_16x16x32_bf16 v[60:63], v[146:149], v[186:189], v[60:63]
	v_mfma_f32_16x16x32_bf16 v[56:59], v[158:161], v[186:189], v[56:59]
	v_mfma_f32_16x16x32_bf16 v[44:47], v[146:149], v[194:197], v[44:47]
	v_mfma_f32_16x16x32_bf16 v[40:43], v[158:161], v[194:197], v[40:43]
	v_mfma_f32_16x16x32_bf16 v[28:31], v[146:149], v[202:205], v[28:31]
	v_mfma_f32_16x16x32_bf16 v[24:27], v[158:161], v[202:205], v[24:27]
	v_mfma_f32_16x16x32_bf16 v[12:15], v[146:149], v[210:213], v[12:15]
	v_mfma_f32_16x16x32_bf16 v[8:11], v[158:161], v[210:213], v[8:11]
	v_mfma_f32_16x16x32_bf16 v[60:63], v[150:153], v[190:193], v[60:63]
	v_mfma_f32_16x16x32_bf16 v[56:59], v[162:165], v[190:193], v[56:59]
	v_mfma_f32_16x16x32_bf16 v[44:47], v[150:153], v[198:201], v[44:47]
	v_mfma_f32_16x16x32_bf16 v[40:43], v[162:165], v[198:201], v[40:43]
	v_mfma_f32_16x16x32_bf16 v[28:31], v[150:153], v[206:209], v[28:31]
	v_mfma_f32_16x16x32_bf16 v[24:27], v[162:165], v[206:209], v[24:27]
	v_mfma_f32_16x16x32_bf16 v[12:15], v[150:153], v[214:217], v[12:15]
	v_mfma_f32_16x16x32_bf16 v[8:11], v[162:165], v[214:217], v[8:11]
	s_setprio 0
	s_setprio 1
	v_mfma_f32_16x16x32_bf16 v[52:55], v[166:169], v[186:189], v[52:55]
	v_mfma_f32_16x16x32_bf16 v[48:51], v[174:177], v[186:189], v[48:51]
	v_mfma_f32_16x16x32_bf16 v[36:39], v[166:169], v[194:197], v[36:39]
	v_mfma_f32_16x16x32_bf16 v[32:35], v[174:177], v[194:197], v[32:35]
	v_mfma_f32_16x16x32_bf16 v[20:23], v[166:169], v[202:205], v[20:23]
	v_mfma_f32_16x16x32_bf16 v[16:19], v[174:177], v[202:205], v[16:19]
	v_mfma_f32_16x16x32_bf16 v[4:7], v[166:169], v[210:213], v[4:7]
	v_mfma_f32_16x16x32_bf16 v[0:3], v[174:177], v[210:213], v[0:3]
	v_mfma_f32_16x16x32_bf16 v[52:55], v[170:173], v[190:193], v[52:55]
	v_mfma_f32_16x16x32_bf16 v[48:51], v[182:185], v[190:193], v[48:51]
	v_mfma_f32_16x16x32_bf16 v[36:39], v[170:173], v[198:201], v[36:39]
	v_mfma_f32_16x16x32_bf16 v[32:35], v[182:185], v[198:201], v[32:35]
	v_mfma_f32_16x16x32_bf16 v[20:23], v[170:173], v[206:209], v[20:23]
	v_mfma_f32_16x16x32_bf16 v[16:19], v[182:185], v[206:209], v[16:19]
	v_mfma_f32_16x16x32_bf16 v[4:7], v[170:173], v[214:217], v[4:7]
	v_mfma_f32_16x16x32_bf16 v[0:3], v[182:185], v[214:217], v[0:3]
	s_setprio 0
	s_barrier
	s_add_i32 s72, 0, 0x18000
	v_add_u32_e32 v136, s72, v154
	s_add_i32 s73, 0, 0x1c000
	ds_read_b128 v[146:149], v136
	ds_read_b128 v[150:153], v136 offset:1024
	ds_read_b128 v[158:161], v136 offset:2048
	ds_read_b128 v[162:165], v136 offset:3072
	v_add_u32_e32 v136, s73, v154
	ds_read_b128 v[166:169], v136
	ds_read_b128 v[170:173], v136 offset:1024
	ds_read_b128 v[174:177], v136 offset:2048
	ds_read_b128 v[182:185], v136 offset:3072
	s_add_u32 s52, s52, 0x40000
	s_addc_u32 s53, s53, 0
	s_mov_b32 m0, s58
	v_lshl_add_u64 v[224:225], s[52:53], 0, v[128:129]
	ds_read_b128 v[186:189], v157 offset:32768
	ds_read_b128 v[190:193], v157 offset:33792
	ds_read_b128 v[194:197], v157 offset:34816
	ds_read_b128 v[198:201], v157 offset:35840
	ds_read_b128 v[202:205], v157 offset:36864
	ds_read_b128 v[206:209], v157 offset:37888
	ds_read_b128 v[210:213], v157 offset:38912
	ds_read_b128 v[214:217], v157 offset:39936
	global_load_lds_dwordx4 v[224:225], off
	v_lshl_add_u64 v[224:225], s[52:53], 0, v[132:133]
	s_mov_b32 m0, s59
	s_nop 0
	global_load_lds_dwordx4 v[224:225], off
	s_waitcnt vmcnt(8)
	s_waitcnt lgkmcnt(0)
	s_barrier
	s_setprio 1
	s_waitcnt lgkmcnt(0)
	v_mfma_f32_16x16x32_bf16 v[124:127], v[146:149], v[186:189], v[124:127]
	v_mfma_f32_16x16x32_bf16 v[120:123], v[158:161], v[186:189], v[120:123]
	v_mfma_f32_16x16x32_bf16 v[108:111], v[146:149], v[194:197], v[108:111]
	v_mfma_f32_16x16x32_bf16 v[104:107], v[158:161], v[194:197], v[104:107]
	v_mfma_f32_16x16x32_bf16 v[92:95], v[146:149], v[202:205], v[92:95]
	v_mfma_f32_16x16x32_bf16 v[88:91], v[158:161], v[202:205], v[88:91]
	v_mfma_f32_16x16x32_bf16 v[76:79], v[146:149], v[210:213], v[76:79]
	v_mfma_f32_16x16x32_bf16 v[72:75], v[158:161], v[210:213], v[72:75]
	v_mfma_f32_16x16x32_bf16 v[124:127], v[150:153], v[190:193], v[124:127]
	v_mfma_f32_16x16x32_bf16 v[120:123], v[162:165], v[190:193], v[120:123]
	v_mfma_f32_16x16x32_bf16 v[108:111], v[150:153], v[198:201], v[108:111]
	v_mfma_f32_16x16x32_bf16 v[104:107], v[162:165], v[198:201], v[104:107]
	v_mfma_f32_16x16x32_bf16 v[92:95], v[150:153], v[206:209], v[92:95]
	v_mfma_f32_16x16x32_bf16 v[88:91], v[162:165], v[206:209], v[88:91]
	v_mfma_f32_16x16x32_bf16 v[76:79], v[150:153], v[214:217], v[76:79]
	v_mfma_f32_16x16x32_bf16 v[72:75], v[162:165], v[214:217], v[72:75]
	s_setprio 0
	s_setprio 1
	v_mfma_f32_16x16x32_bf16 v[116:119], v[166:169], v[186:189], v[116:119]
	v_mfma_f32_16x16x32_bf16 v[112:115], v[174:177], v[186:189], v[112:115]
	v_mfma_f32_16x16x32_bf16 v[100:103], v[166:169], v[194:197], v[100:103]
	v_mfma_f32_16x16x32_bf16 v[96:99], v[174:177], v[194:197], v[96:99]
	v_mfma_f32_16x16x32_bf16 v[84:87], v[166:169], v[202:205], v[84:87]
	v_mfma_f32_16x16x32_bf16 v[80:83], v[174:177], v[202:205], v[80:83]
	v_mfma_f32_16x16x32_bf16 v[68:71], v[166:169], v[210:213], v[68:71]
	v_mfma_f32_16x16x32_bf16 v[64:67], v[174:177], v[210:213], v[64:67]
	v_mfma_f32_16x16x32_bf16 v[116:119], v[170:173], v[190:193], v[116:119]
	v_mfma_f32_16x16x32_bf16 v[112:115], v[182:185], v[190:193], v[112:115]
	v_mfma_f32_16x16x32_bf16 v[100:103], v[170:173], v[198:201], v[100:103]
	v_mfma_f32_16x16x32_bf16 v[96:99], v[182:185], v[198:201], v[96:99]
	v_mfma_f32_16x16x32_bf16 v[84:87], v[170:173], v[206:209], v[84:87]
	v_mfma_f32_16x16x32_bf16 v[80:83], v[182:185], v[206:209], v[80:83]
	v_mfma_f32_16x16x32_bf16 v[68:71], v[170:173], v[214:217], v[68:71]
	v_mfma_f32_16x16x32_bf16 v[64:67], v[182:185], v[214:217], v[64:67]
	s_setprio 0
	s_barrier
	s_add_i32 s52, s72, s55
	v_lshl_add_u64 v[178:179], v[178:179], 0, s[0:1]
	s_mov_b32 m0, s52
	ds_read_b128 v[186:189], v157 offset:49152
	ds_read_b128 v[190:193], v157 offset:50176
	ds_read_b128 v[194:197], v157 offset:51200
	ds_read_b128 v[198:201], v157 offset:52224
	ds_read_b128 v[202:205], v157 offset:53248
	ds_read_b128 v[206:209], v157 offset:54272
	ds_read_b128 v[210:213], v157 offset:55296
	ds_read_b128 v[214:217], v157 offset:56320
	global_load_lds_dwordx4 v[178:179], off
	s_add_i32 m0, s52, 0x2000
	s_add_u32 s50, s50, 0x40080
	v_lshl_add_u64 v[178:179], v[218:219], 0, s[0:1]
	s_addc_u32 s51, s51, 0
	s_add_i32 s52, s73, s55
	global_load_lds_dwordx4 v[178:179], off
	v_lshl_add_u64 v[178:179], s[50:51], 0, v[130:131]
	s_mov_b32 m0, s52
	s_nop 0
	global_load_lds_dwordx4 v[178:179], off
	v_lshl_add_u64 v[178:179], s[50:51], 0, v[134:135]
	s_add_i32 m0, s52, 0x2000
	s_nop 0
	global_load_lds_dwordx4 v[178:179], off
	v_lshl_add_u64 v[178:179], v[220:221], 0, s[0:1]
	s_mov_b32 m0, s62
	s_nop 0
	global_load_lds_dwordx4 v[178:179], off
	v_lshl_add_u64 v[178:179], v[222:223], 0, s[0:1]
	s_mov_b32 m0, s63
	s_nop 0
	global_load_lds_dwordx4 v[178:179], off
	s_waitcnt vmcnt(8)
	s_waitcnt lgkmcnt(0)
	s_barrier
	s_setprio 1
	s_waitcnt lgkmcnt(0)
	v_mfma_f32_16x16x32_bf16 v[60:63], v[146:149], v[186:189], v[60:63]
	v_mfma_f32_16x16x32_bf16 v[56:59], v[158:161], v[186:189], v[56:59]
	v_mfma_f32_16x16x32_bf16 v[44:47], v[146:149], v[194:197], v[44:47]
	v_mfma_f32_16x16x32_bf16 v[40:43], v[158:161], v[194:197], v[40:43]
	v_mfma_f32_16x16x32_bf16 v[28:31], v[146:149], v[202:205], v[28:31]
	v_mfma_f32_16x16x32_bf16 v[24:27], v[158:161], v[202:205], v[24:27]
	v_mfma_f32_16x16x32_bf16 v[12:15], v[146:149], v[210:213], v[12:15]
	v_mfma_f32_16x16x32_bf16 v[8:11], v[158:161], v[210:213], v[8:11]
	v_mfma_f32_16x16x32_bf16 v[60:63], v[150:153], v[190:193], v[60:63]
	v_mfma_f32_16x16x32_bf16 v[56:59], v[162:165], v[190:193], v[56:59]
	v_mfma_f32_16x16x32_bf16 v[44:47], v[150:153], v[198:201], v[44:47]
	v_mfma_f32_16x16x32_bf16 v[40:43], v[162:165], v[198:201], v[40:43]
	v_mfma_f32_16x16x32_bf16 v[28:31], v[150:153], v[206:209], v[28:31]
	v_mfma_f32_16x16x32_bf16 v[24:27], v[162:165], v[206:209], v[24:27]
	v_mfma_f32_16x16x32_bf16 v[12:15], v[150:153], v[214:217], v[12:15]
	v_mfma_f32_16x16x32_bf16 v[8:11], v[162:165], v[214:217], v[8:11]
	s_setprio 0
	s_setprio 1
	v_mfma_f32_16x16x32_bf16 v[52:55], v[166:169], v[186:189], v[52:55]
	v_mfma_f32_16x16x32_bf16 v[48:51], v[174:177], v[186:189], v[48:51]
	v_mfma_f32_16x16x32_bf16 v[36:39], v[166:169], v[194:197], v[36:39]
	v_mfma_f32_16x16x32_bf16 v[32:35], v[174:177], v[194:197], v[32:35]
	v_mfma_f32_16x16x32_bf16 v[20:23], v[166:169], v[202:205], v[20:23]
	v_mfma_f32_16x16x32_bf16 v[16:19], v[174:177], v[202:205], v[16:19]
	v_mfma_f32_16x16x32_bf16 v[4:7], v[166:169], v[210:213], v[4:7]
	v_mfma_f32_16x16x32_bf16 v[0:3], v[174:177], v[210:213], v[0:3]
	v_mfma_f32_16x16x32_bf16 v[52:55], v[170:173], v[190:193], v[52:55]
	v_mfma_f32_16x16x32_bf16 v[48:51], v[182:185], v[190:193], v[48:51]
	v_mfma_f32_16x16x32_bf16 v[36:39], v[170:173], v[198:201], v[36:39]
	v_mfma_f32_16x16x32_bf16 v[32:35], v[182:185], v[198:201], v[32:35]
	v_mfma_f32_16x16x32_bf16 v[20:23], v[170:173], v[206:209], v[20:23]
	v_mfma_f32_16x16x32_bf16 v[16:19], v[182:185], v[206:209], v[16:19]
	v_mfma_f32_16x16x32_bf16 v[4:7], v[170:173], v[214:217], v[4:7]
	v_mfma_f32_16x16x32_bf16 v[0:3], v[182:185], v[214:217], v[0:3]
	s_setprio 0
	s_add_i32 s71, s71, 2
	s_add_u32 s48, s48, 0x100
	s_addc_u32 s49, s49, 0
	s_add_u32 s69, s69, 0x100
	s_addc_u32 s70, s70, 0
	s_cmp_gt_u32 s71, 13
	s_barrier
	s_cbranch_scc0 .LBB0_225
	s_and_b64 vcc, exec, s[24:25]
	s_cbranch_vccz .LBB0_228
	s_barrier

.Lmm_5_7:
	s_setprio 0
	s_add_i32 s53, s53, 2
	s_add_u32 s26, s26, 0x100
	s_addc_u32 s27, s27, 0
	s_add_u32 s51, s51, 0x100
	s_addc_u32 s52, s52, 0
	s_cmp_gt_u32 s53, 5
	s_barrier
	s_cbranch_scc0 .LBB0_1404
	s_and_b64 vcc, exec, s[16:17]
	s_cbranch_vccz .LBB0_1407
	s_barrier

.Lmm_6_7:
	s_setprio 0
	s_add_i32 s68, s68, 2
	s_add_u32 s36, s36, 0x100
	s_addc_u32 s37, s37, 0
	s_add_u32 s66, s66, 0x100
	s_addc_u32 s67, s67, 0
	s_cmp_gt_u32 s68, 13
	s_barrier
	s_cbranch_scc0 .Lqk_6
	s_branch .Lqk_join_6

.LBB0_1436:
	ds_read_b128 v[128:131], v165
	ds_read_b128 v[132:135], v165 offset:1024
	ds_read_b128 v[136:139], v165 offset:2048
	ds_read_b128 v[140:143], v165 offset:3072
	ds_read_b128 v[156:159], v166
	ds_read_b128 v[160:163], v166 offset:1024
	ds_read_b128 v[170:173], v166 offset:2048
	ds_read_b128 v[174:177], v166 offset:3072
	s_add_u32 s38, s36, 0xfffc0080
	s_addc_u32 s39, s37, -1
	s_cmp_eq_u32 s68, 12
	s_cselect_b32 s41, s9, s39
	s_cselect_b32 s40, s27, s38
	s_cselect_b32 s39, s25, s67
	s_cselect_b32 s38, s65, s66
	v_lshl_add_u64 v[178:179], s[36:37], 0, v[148:149]
	s_add_i32 m0, s35, 0xc000
	ds_read_b128 v[182:185], v167
	ds_read_b128 v[186:189], v167 offset:1024
	ds_read_b128 v[190:193], v167 offset:2048
	ds_read_b128 v[194:197], v167 offset:3072
	ds_read_b128 v[198:201], v167 offset:4096
	ds_read_b128 v[202:205], v167 offset:5120
	ds_read_b128 v[206:209], v167 offset:6144
	ds_read_b128 v[210:213], v167 offset:7168
	global_load_lds_dwordx4 v[178:179], off
	v_lshl_add_u64 v[178:179], s[36:37], 0, v[150:151]
	s_add_i32 m0, s35, 0xe000
	s_nop 0
	global_load_lds_dwordx4 v[178:179], off
	s_waitcnt vmcnt(8)
	s_waitcnt lgkmcnt(0)
	s_barrier
	s_setprio 1
	s_waitcnt lgkmcnt(0)
	v_mfma_f32_16x16x32_bf16 v[124:127], v[128:131], v[182:185], v[124:127]
	v_mfma_f32_16x16x32_bf16 v[120:123], v[136:139], v[182:185], v[120:123]
	v_mfma_f32_16x16x32_bf16 v[108:111], v[128:131], v[190:193], v[108:111]
	v_mfma_f32_16x16x32_bf16 v[104:107], v[136:139], v[190:193], v[104:107]
	v_mfma_f32_16x16x32_bf16 v[92:95], v[128:131], v[198:201], v[92:95]
	v_mfma_f32_16x16x32_bf16 v[88:91], v[136:139], v[198:201], v[88:91]
	v_mfma_f32_16x16x32_bf16 v[76:79], v[128:131], v[206:209], v[76:79]
	v_mfma_f32_16x16x32_bf16 v[72:75], v[136:139], v[206:209], v[72:75]
	v_mfma_f32_16x16x32_bf16 v[124:127], v[132:135], v[186:189], v[124:127]
	v_mfma_f32_16x16x32_bf16 v[120:123], v[140:143], v[186:189], v[120:123]
	v_mfma_f32_16x16x32_bf16 v[108:111], v[132:135], v[194:197], v[108:111]
	v_mfma_f32_16x16x32_bf16 v[104:107], v[140:143], v[194:197], v[104:107]
	v_mfma_f32_16x16x32_bf16 v[92:95], v[132:135], v[202:205], v[92:95]
	v_mfma_f32_16x16x32_bf16 v[88:91], v[140:143], v[202:205], v[88:91]
	v_mfma_f32_16x16x32_bf16 v[76:79], v[132:135], v[210:213], v[76:79]
	v_mfma_f32_16x16x32_bf16 v[72:75], v[140:143], v[210:213], v[72:75]
	s_setprio 0
	s_setprio 1
	v_mfma_f32_16x16x32_bf16 v[116:119], v[156:159], v[182:185], v[116:119]
	v_mfma_f32_16x16x32_bf16 v[112:115], v[170:173], v[182:185], v[112:115]
	v_mfma_f32_16x16x32_bf16 v[100:103], v[156:159], v[190:193], v[100:103]
	v_mfma_f32_16x16x32_bf16 v[96:99], v[170:173], v[190:193], v[96:99]
	v_mfma_f32_16x16x32_bf16 v[84:87], v[156:159], v[198:201], v[84:87]
	v_mfma_f32_16x16x32_bf16 v[80:83], v[170:173], v[198:201], v[80:83]
	v_mfma_f32_16x16x32_bf16 v[68:71], v[156:159], v[206:209], v[68:71]
	v_mfma_f32_16x16x32_bf16 v[64:67], v[170:173], v[206:209], v[64:67]
	v_mfma_f32_16x16x32_bf16 v[116:119], v[160:163], v[186:189], v[116:119]
	v_mfma_f32_16x16x32_bf16 v[112:115], v[174:177], v[186:189], v[112:115]
	v_mfma_f32_16x16x32_bf16 v[100:103], v[160:163], v[194:197], v[100:103]
	v_mfma_f32_16x16x32_bf16 v[96:99], v[174:177], v[194:197], v[96:99]
	v_mfma_f32_16x16x32_bf16 v[84:87], v[160:163], v[202:205], v[84:87]
	v_mfma_f32_16x16x32_bf16 v[80:83], v[174:177], v[202:205], v[80:83]
	v_mfma_f32_16x16x32_bf16 v[68:71], v[160:163], v[210:213], v[68:71]
	v_mfma_f32_16x16x32_bf16 v[64:67], v[174:177], v[210:213], v[64:67]
	s_setprio 0
	s_barrier
	s_add_i32 s69, s58, s48
	v_lshl_add_u64 v[178:179], s[38:39], 0, v[144:145]
	s_mov_b32 m0, s69
	ds_read_b128 v[182:185], v167 offset:16384
	ds_read_b128 v[186:189], v167 offset:17408
	ds_read_b128 v[190:193], v167 offset:18432
	ds_read_b128 v[194:197], v167 offset:19456
	ds_read_b128 v[198:201], v167 offset:20480
	ds_read_b128 v[202:205], v167 offset:21504
	ds_read_b128 v[206:209], v167 offset:22528
	ds_read_b128 v[210:213], v167 offset:23552
	global_load_lds_dwordx4 v[178:179], off
	s_add_i32 m0, s69, 0x2000
	s_add_u32 s70, s38, 0x40000
	v_lshl_add_u64 v[214:215], s[38:39], 0, v[146:147]
	s_addc_u32 s71, s39, 0
	s_add_i32 s69, s59, s48
	global_load_lds_dwordx4 v[214:215], off
	v_lshl_add_u64 v[216:217], s[70:71], 0, v[144:145]
	s_mov_b32 m0, s69
	v_lshl_add_u64 v[218:219], s[40:41], 0, v[146:147]
	global_load_lds_dwordx4 v[216:217], off
	v_lshl_add_u64 v[216:217], s[70:71], 0, v[146:147]
	s_add_i32 m0, s69, 0x2000
	s_nop 0
	global_load_lds_dwordx4 v[216:217], off
	v_lshl_add_u64 v[216:217], s[40:41], 0, v[144:145]
	s_mov_b32 m0, s35
	s_nop 0
	global_load_lds_dwordx4 v[216:217], off
	s_mov_b32 m0, s49
	s_nop 0
	global_load_lds_dwordx4 v[218:219], off
	s_waitcnt vmcnt(8)
	s_waitcnt lgkmcnt(0)
	s_barrier
	s_setprio 1
	s_waitcnt lgkmcnt(0)
	v_mfma_f32_16x16x32_bf16 v[60:63], v[128:131], v[182:185], v[60:63]
	v_mfma_f32_16x16x32_bf16 v[56:59], v[136:139], v[182:185], v[56:59]
	v_mfma_f32_16x16x32_bf16 v[44:47], v[128:131], v[190:193], v[44:47]
	v_mfma_f32_16x16x32_bf16 v[40:43], v[136:139], v[190:193], v[40:43]
	v_mfma_f32_16x16x32_bf16 v[28:31], v[128:131], v[198:201], v[28:31]
	v_mfma_f32_16x16x32_bf16 v[24:27], v[136:139], v[198:201], v[24:27]
	v_mfma_f32_16x16x32_bf16 v[12:15], v[128:131], v[206:209], v[12:15]
	v_mfma_f32_16x16x32_bf16 v[8:11], v[136:139], v[206:209], v[8:11]
	v_mfma_f32_16x16x32_bf16 v[60:63], v[132:135], v[186:189], v[60:63]
	v_mfma_f32_16x16x32_bf16 v[56:59], v[140:143], v[186:189], v[56:59]
	v_mfma_f32_16x16x32_bf16 v[44:47], v[132:135], v[194:197], v[44:47]
	v_mfma_f32_16x16x32_bf16 v[40:43], v[140:143], v[194:197], v[40:43]
	v_mfma_f32_16x16x32_bf16 v[28:31], v[132:135], v[202:205], v[28:31]
	v_mfma_f32_16x16x32_bf16 v[24:27], v[140:143], v[202:205], v[24:27]
	v_mfma_f32_16x16x32_bf16 v[12:15], v[132:135], v[210:213], v[12:15]
	v_mfma_f32_16x16x32_bf16 v[8:11], v[140:143], v[210:213], v[8:11]
	s_setprio 0
	s_setprio 1
	v_mfma_f32_16x16x32_bf16 v[52:55], v[156:159], v[182:185], v[52:55]
	v_mfma_f32_16x16x32_bf16 v[48:51], v[170:173], v[182:185], v[48:51]
	v_mfma_f32_16x16x32_bf16 v[36:39], v[156:159], v[190:193], v[36:39]
	v_mfma_f32_16x16x32_bf16 v[32:35], v[170:173], v[190:193], v[32:35]
	v_mfma_f32_16x16x32_bf16 v[20:23], v[156:159], v[198:201], v[20:23]
	v_mfma_f32_16x16x32_bf16 v[16:19], v[170:173], v[198:201], v[16:19]
	v_mfma_f32_16x16x32_bf16 v[4:7], v[156:159], v[206:209], v[4:7]
	v_mfma_f32_16x16x32_bf16 v[0:3], v[170:173], v[206:209], v[0:3]
	v_mfma_f32_16x16x32_bf16 v[52:55], v[160:163], v[186:189], v[52:55]
	v_mfma_f32_16x16x32_bf16 v[48:51], v[174:177], v[186:189], v[48:51]
	v_mfma_f32_16x16x32_bf16 v[36:39], v[160:163], v[194:197], v[36:39]
	v_mfma_f32_16x16x32_bf16 v[32:35], v[174:177], v[194:197], v[32:35]
	v_mfma_f32_16x16x32_bf16 v[20:23], v[160:163], v[202:205], v[20:23]
	v_mfma_f32_16x16x32_bf16 v[16:19], v[174:177], v[202:205], v[16:19]
	v_mfma_f32_16x16x32_bf16 v[4:7], v[160:163], v[210:213], v[4:7]
	v_mfma_f32_16x16x32_bf16 v[0:3], v[174:177], v[210:213], v[0:3]
	s_setprio 0
	s_barrier
	s_add_i32 s69, 0, 0x18000
	s_add_i32 s70, 0, 0x1c000
	v_add_u32_e32 v140, s69, v164
	v_add_u32_e32 v169, s70, v164
	ds_read_b128 v[128:131], v140
	ds_read_b128 v[132:135], v140 offset:1024
	ds_read_b128 v[136:139], v140 offset:2048
	ds_read_b128 v[140:143], v140 offset:3072
	ds_read_b128 v[156:159], v169
	ds_read_b128 v[160:163], v169 offset:1024
	ds_read_b128 v[170:173], v169 offset:2048
	ds_read_b128 v[174:177], v169 offset:3072
	s_add_u32 s40, s40, 0x40000
	s_addc_u32 s41, s41, 0
	s_mov_b32 m0, s50
	v_lshl_add_u64 v[220:221], s[40:41], 0, v[144:145]
	ds_read_b128 v[182:185], v167 offset:32768
	ds_read_b128 v[186:189], v167 offset:33792
	ds_read_b128 v[190:193], v167 offset:34816
	ds_read_b128 v[194:197], v167 offset:35840
	ds_read_b128 v[198:201], v167 offset:36864
	ds_read_b128 v[202:205], v167 offset:37888
	ds_read_b128 v[206:209], v167 offset:38912
	ds_read_b128 v[210:213], v167 offset:39936
	global_load_lds_dwordx4 v[220:221], off
	v_lshl_add_u64 v[220:221], s[40:41], 0, v[146:147]
	s_mov_b32 m0, s51
	s_nop 0
	global_load_lds_dwordx4 v[220:221], off
	s_waitcnt vmcnt(8)
	s_waitcnt lgkmcnt(0)
	s_barrier
	s_setprio 1
	s_waitcnt lgkmcnt(0)
	v_mfma_f32_16x16x32_bf16 v[124:127], v[128:131], v[182:185], v[124:127]
	v_mfma_f32_16x16x32_bf16 v[120:123], v[136:139], v[182:185], v[120:123]
	v_mfma_f32_16x16x32_bf16 v[108:111], v[128:131], v[190:193], v[108:111]
	v_mfma_f32_16x16x32_bf16 v[104:107], v[136:139], v[190:193], v[104:107]
	v_mfma_f32_16x16x32_bf16 v[92:95], v[128:131], v[198:201], v[92:95]
	v_mfma_f32_16x16x32_bf16 v[88:91], v[136:139], v[198:201], v[88:91]
	v_mfma_f32_16x16x32_bf16 v[76:79], v[128:131], v[206:209], v[76:79]
	v_mfma_f32_16x16x32_bf16 v[72:75], v[136:139], v[206:209], v[72:75]
	v_mfma_f32_16x16x32_bf16 v[124:127], v[132:135], v[186:189], v[124:127]
	v_mfma_f32_16x16x32_bf16 v[120:123], v[140:143], v[186:189], v[120:123]
	v_mfma_f32_16x16x32_bf16 v[108:111], v[132:135], v[194:197], v[108:111]
	v_mfma_f32_16x16x32_bf16 v[104:107], v[140:143], v[194:197], v[104:107]
	v_mfma_f32_16x16x32_bf16 v[92:95], v[132:135], v[202:205], v[92:95]
	v_mfma_f32_16x16x32_bf16 v[88:91], v[140:143], v[202:205], v[88:91]
	v_mfma_f32_16x16x32_bf16 v[76:79], v[132:135], v[210:213], v[76:79]
	v_mfma_f32_16x16x32_bf16 v[72:75], v[140:143], v[210:213], v[72:75]
	s_setprio 0
	s_setprio 1
	v_mfma_f32_16x16x32_bf16 v[116:119], v[156:159], v[182:185], v[116:119]
	v_mfma_f32_16x16x32_bf16 v[112:115], v[170:173], v[182:185], v[112:115]
	v_mfma_f32_16x16x32_bf16 v[100:103], v[156:159], v[190:193], v[100:103]
	v_mfma_f32_16x16x32_bf16 v[96:99], v[170:173], v[190:193], v[96:99]
	v_mfma_f32_16x16x32_bf16 v[84:87], v[156:159], v[198:201], v[84:87]
	v_mfma_f32_16x16x32_bf16 v[80:83], v[170:173], v[198:201], v[80:83]
	v_mfma_f32_16x16x32_bf16 v[68:71], v[156:159], v[206:209], v[68:71]
	v_mfma_f32_16x16x32_bf16 v[64:67], v[170:173], v[206:209], v[64:67]
	v_mfma_f32_16x16x32_bf16 v[116:119], v[160:163], v[186:189], v[116:119]
	v_mfma_f32_16x16x32_bf16 v[112:115], v[174:177], v[186:189], v[112:115]
	v_mfma_f32_16x16x32_bf16 v[100:103], v[160:163], v[194:197], v[100:103]
	v_mfma_f32_16x16x32_bf16 v[96:99], v[174:177], v[194:197], v[96:99]
	v_mfma_f32_16x16x32_bf16 v[84:87], v[160:163], v[202:205], v[84:87]
	v_mfma_f32_16x16x32_bf16 v[80:83], v[174:177], v[202:205], v[80:83]
	v_mfma_f32_16x16x32_bf16 v[68:71], v[160:163], v[210:213], v[68:71]
	v_mfma_f32_16x16x32_bf16 v[64:67], v[174:177], v[210:213], v[64:67]
	s_setprio 0
	s_barrier
	s_add_i32 s40, s69, s48
	v_lshl_add_u64 v[178:179], v[178:179], 0, s[20:21]
	s_mov_b32 m0, s40
	ds_read_b128 v[182:185], v167 offset:49152
	ds_read_b128 v[186:189], v167 offset:50176
	ds_read_b128 v[190:193], v167 offset:51200
	ds_read_b128 v[194:197], v167 offset:52224
	ds_read_b128 v[198:201], v167 offset:53248
	ds_read_b128 v[202:205], v167 offset:54272
	ds_read_b128 v[206:209], v167 offset:55296
	ds_read_b128 v[210:213], v167 offset:56320
	global_load_lds_dwordx4 v[178:179], off
	s_add_i32 m0, s40, 0x2000
	s_add_u32 s38, s38, 0x40080
	v_lshl_add_u64 v[178:179], v[214:215], 0, s[20:21]
	s_addc_u32 s39, s39, 0
	s_add_i32 s40, s70, s48
	global_load_lds_dwordx4 v[178:179], off
	v_lshl_add_u64 v[178:179], s[38:39], 0, v[144:145]
	s_mov_b32 m0, s40
	s_nop 0
	global_load_lds_dwordx4 v[178:179], off
	v_lshl_add_u64 v[178:179], s[38:39], 0, v[146:147]
	s_add_i32 m0, s40, 0x2000
	s_nop 0
	global_load_lds_dwordx4 v[178:179], off
	v_lshl_add_u64 v[178:179], v[216:217], 0, s[20:21]
	s_mov_b32 m0, s56
	s_nop 0
	global_load_lds_dwordx4 v[178:179], off
	v_lshl_add_u64 v[178:179], v[218:219], 0, s[20:21]
	s_mov_b32 m0, s57
	s_nop 0
	global_load_lds_dwordx4 v[178:179], off
	s_waitcnt vmcnt(8)
	s_waitcnt lgkmcnt(0)
	s_barrier
	s_setprio 1
	s_waitcnt lgkmcnt(0)
	v_mfma_f32_16x16x32_bf16 v[60:63], v[128:131], v[182:185], v[60:63]
	v_mfma_f32_16x16x32_bf16 v[56:59], v[136:139], v[182:185], v[56:59]
	v_mfma_f32_16x16x32_bf16 v[44:47], v[128:131], v[190:193], v[44:47]
	v_mfma_f32_16x16x32_bf16 v[40:43], v[136:139], v[190:193], v[40:43]
	v_mfma_f32_16x16x32_bf16 v[28:31], v[128:131], v[198:201], v[28:31]
	v_mfma_f32_16x16x32_bf16 v[24:27], v[136:139], v[198:201], v[24:27]
	v_mfma_f32_16x16x32_bf16 v[12:15], v[128:131], v[206:209], v[12:15]
	v_mfma_f32_16x16x32_bf16 v[8:11], v[136:139], v[206:209], v[8:11]
	v_mfma_f32_16x16x32_bf16 v[60:63], v[132:135], v[186:189], v[60:63]
	v_mfma_f32_16x16x32_bf16 v[56:59], v[140:143], v[186:189], v[56:59]
	v_mfma_f32_16x16x32_bf16 v[44:47], v[132:135], v[194:197], v[44:47]
	v_mfma_f32_16x16x32_bf16 v[40:43], v[140:143], v[194:197], v[40:43]
	v_mfma_f32_16x16x32_bf16 v[28:31], v[132:135], v[202:205], v[28:31]
	v_mfma_f32_16x16x32_bf16 v[24:27], v[140:143], v[202:205], v[24:27]
	v_mfma_f32_16x16x32_bf16 v[12:15], v[132:135], v[210:213], v[12:15]
	v_mfma_f32_16x16x32_bf16 v[8:11], v[140:143], v[210:213], v[8:11]
	s_setprio 0
	s_setprio 1
	v_mfma_f32_16x16x32_bf16 v[52:55], v[156:159], v[182:185], v[52:55]
	v_mfma_f32_16x16x32_bf16 v[48:51], v[170:173], v[182:185], v[48:51]
	v_mfma_f32_16x16x32_bf16 v[36:39], v[156:159], v[190:193], v[36:39]
	v_mfma_f32_16x16x32_bf16 v[32:35], v[170:173], v[190:193], v[32:35]
	v_mfma_f32_16x16x32_bf16 v[20:23], v[156:159], v[198:201], v[20:23]
	v_mfma_f32_16x16x32_bf16 v[16:19], v[170:173], v[198:201], v[16:19]
	v_mfma_f32_16x16x32_bf16 v[4:7], v[156:159], v[206:209], v[4:7]
	v_mfma_f32_16x16x32_bf16 v[0:3], v[170:173], v[206:209], v[0:3]
	v_mfma_f32_16x16x32_bf16 v[52:55], v[160:163], v[186:189], v[52:55]
	v_mfma_f32_16x16x32_bf16 v[48:51], v[174:177], v[186:189], v[48:51]
	v_mfma_f32_16x16x32_bf16 v[36:39], v[160:163], v[194:197], v[36:39]
	v_mfma_f32_16x16x32_bf16 v[32:35], v[174:177], v[194:197], v[32:35]
	v_mfma_f32_16x16x32_bf16 v[20:23], v[160:163], v[202:205], v[20:23]
	v_mfma_f32_16x16x32_bf16 v[16:19], v[174:177], v[202:205], v[16:19]
	v_mfma_f32_16x16x32_bf16 v[4:7], v[160:163], v[210:213], v[4:7]
	v_mfma_f32_16x16x32_bf16 v[0:3], v[174:177], v[210:213], v[0:3]
	s_setprio 0
	s_add_i32 s68, s68, 2
	s_add_u32 s36, s36, 0x100
	s_addc_u32 s37, s37, 0
	s_add_u32 s66, s66, 0x100
	s_addc_u32 s67, s67, 0
	s_cmp_gt_u32 s68, 13
	s_barrier
	s_cbranch_scc0 .LBB0_1436

.LBB0_1482:
	ds_read_b128 v[144:147], v155
	ds_read_b128 v[148:151], v155 offset:1024
	ds_read_b128 v[160:163], v155 offset:2048
	ds_read_b128 v[164:167], v155 offset:3072
	ds_read_b128 v[168:171], v156
	ds_read_b128 v[172:175], v156 offset:1024
	ds_read_b128 v[176:179], v156 offset:2048
	ds_read_b128 v[182:185], v156 offset:3072
	s_add_u32 s34, s30, 0xfffc0080
	s_addc_u32 s35, s31, -1
	s_cmp_eq_u32 s65, 12
	s_cselect_b32 s37, s25, s35
	s_cselect_b32 s36, s58, s34
	s_cselect_b32 s35, s23, s64
	s_cselect_b32 s34, s59, s63
	v_lshl_add_u64 v[152:153], s[30:31], 0, v[136:137]
	s_add_i32 m0, s43, 0xc000
	ds_read_b128 v[186:189], v157
	ds_read_b128 v[190:193], v157 offset:1024
	ds_read_b128 v[194:197], v157 offset:2048
	ds_read_b128 v[198:201], v157 offset:3072
	ds_read_b128 v[202:205], v157 offset:4096
	ds_read_b128 v[206:209], v157 offset:5120
	ds_read_b128 v[210:213], v157 offset:6144
	ds_read_b128 v[214:217], v157 offset:7168
	global_load_lds_dwordx4 v[152:153], off
	v_lshl_add_u64 v[152:153], s[30:31], 0, v[138:139]
	s_add_i32 m0, s43, 0xe000
	s_nop 0
	global_load_lds_dwordx4 v[152:153], off
	s_waitcnt vmcnt(8)
	s_waitcnt lgkmcnt(0)
	s_barrier
	s_setprio 1
	s_waitcnt lgkmcnt(0)
	v_mfma_f32_16x16x32_bf16 v[124:127], v[144:147], v[186:189], v[124:127]
	v_mfma_f32_16x16x32_bf16 v[120:123], v[160:163], v[186:189], v[120:123]
	v_mfma_f32_16x16x32_bf16 v[108:111], v[144:147], v[194:197], v[108:111]
	v_mfma_f32_16x16x32_bf16 v[104:107], v[160:163], v[194:197], v[104:107]
	v_mfma_f32_16x16x32_bf16 v[92:95], v[144:147], v[202:205], v[92:95]
	v_mfma_f32_16x16x32_bf16 v[88:91], v[160:163], v[202:205], v[88:91]
	v_mfma_f32_16x16x32_bf16 v[76:79], v[144:147], v[210:213], v[76:79]
	v_mfma_f32_16x16x32_bf16 v[72:75], v[160:163], v[210:213], v[72:75]
	v_mfma_f32_16x16x32_bf16 v[124:127], v[148:151], v[190:193], v[124:127]
	v_mfma_f32_16x16x32_bf16 v[120:123], v[164:167], v[190:193], v[120:123]
	v_mfma_f32_16x16x32_bf16 v[108:111], v[148:151], v[198:201], v[108:111]
	v_mfma_f32_16x16x32_bf16 v[104:107], v[164:167], v[198:201], v[104:107]
	v_mfma_f32_16x16x32_bf16 v[92:95], v[148:151], v[206:209], v[92:95]
	v_mfma_f32_16x16x32_bf16 v[88:91], v[164:167], v[206:209], v[88:91]
	v_mfma_f32_16x16x32_bf16 v[76:79], v[148:151], v[214:217], v[76:79]
	v_mfma_f32_16x16x32_bf16 v[72:75], v[164:167], v[214:217], v[72:75]
	s_setprio 0
	s_setprio 1
	v_mfma_f32_16x16x32_bf16 v[116:119], v[168:171], v[186:189], v[116:119]
	v_mfma_f32_16x16x32_bf16 v[112:115], v[176:179], v[186:189], v[112:115]
	v_mfma_f32_16x16x32_bf16 v[100:103], v[168:171], v[194:197], v[100:103]
	v_mfma_f32_16x16x32_bf16 v[96:99], v[176:179], v[194:197], v[96:99]
	v_mfma_f32_16x16x32_bf16 v[84:87], v[168:171], v[202:205], v[84:87]
	v_mfma_f32_16x16x32_bf16 v[80:83], v[176:179], v[202:205], v[80:83]
	v_mfma_f32_16x16x32_bf16 v[68:71], v[168:171], v[210:213], v[68:71]
	v_mfma_f32_16x16x32_bf16 v[64:67], v[176:179], v[210:213], v[64:67]
	v_mfma_f32_16x16x32_bf16 v[116:119], v[172:175], v[190:193], v[116:119]
	v_mfma_f32_16x16x32_bf16 v[112:115], v[182:185], v[190:193], v[112:115]
	v_mfma_f32_16x16x32_bf16 v[100:103], v[172:175], v[198:201], v[100:103]
	v_mfma_f32_16x16x32_bf16 v[96:99], v[182:185], v[198:201], v[96:99]
	v_mfma_f32_16x16x32_bf16 v[84:87], v[172:175], v[206:209], v[84:87]
	v_mfma_f32_16x16x32_bf16 v[80:83], v[182:185], v[206:209], v[80:83]
	v_mfma_f32_16x16x32_bf16 v[68:71], v[172:175], v[214:217], v[68:71]
	v_mfma_f32_16x16x32_bf16 v[64:67], v[182:185], v[214:217], v[64:67]
	s_setprio 0
	s_barrier
	s_add_i32 s66, s54, s42
	v_lshl_add_u64 v[152:153], s[34:35], 0, v[132:133]
	s_mov_b32 m0, s66
	ds_read_b128 v[186:189], v157 offset:16384
	ds_read_b128 v[190:193], v157 offset:17408
	ds_read_b128 v[194:197], v157 offset:18432
	ds_read_b128 v[198:201], v157 offset:19456
	ds_read_b128 v[202:205], v157 offset:20480
	ds_read_b128 v[206:209], v157 offset:21504
	ds_read_b128 v[210:213], v157 offset:22528
	ds_read_b128 v[214:217], v157 offset:23552
	global_load_lds_dwordx4 v[152:153], off
	s_add_i32 m0, s66, 0x2000
	s_add_u32 s66, s34, 0x40000
	v_lshl_add_u64 v[218:219], s[34:35], 0, v[128:129]
	s_addc_u32 s67, s35, 0
	s_add_i32 s68, s55, s42
	global_load_lds_dwordx4 v[218:219], off
	v_lshl_add_u64 v[220:221], s[66:67], 0, v[132:133]
	s_mov_b32 m0, s68
	v_lshl_add_u64 v[222:223], s[36:37], 0, v[130:131]
	global_load_lds_dwordx4 v[220:221], off
	v_lshl_add_u64 v[220:221], s[66:67], 0, v[128:129]
	s_add_i32 m0, s68, 0x2000
	s_nop 0
	global_load_lds_dwordx4 v[220:221], off
	v_lshl_add_u64 v[220:221], s[36:37], 0, v[134:135]
	s_mov_b32 m0, s43
	s_nop 0
	global_load_lds_dwordx4 v[220:221], off
	s_mov_b32 m0, s44
	s_nop 0
	global_load_lds_dwordx4 v[222:223], off
	s_waitcnt vmcnt(8)
	s_waitcnt lgkmcnt(0)
	s_barrier
	s_setprio 1
	s_waitcnt lgkmcnt(0)
	v_mfma_f32_16x16x32_bf16 v[60:63], v[144:147], v[186:189], v[60:63]
	v_mfma_f32_16x16x32_bf16 v[56:59], v[160:163], v[186:189], v[56:59]
	v_mfma_f32_16x16x32_bf16 v[44:47], v[144:147], v[194:197], v[44:47]
	v_mfma_f32_16x16x32_bf16 v[40:43], v[160:163], v[194:197], v[40:43]
	v_mfma_f32_16x16x32_bf16 v[28:31], v[144:147], v[202:205], v[28:31]
	v_mfma_f32_16x16x32_bf16 v[24:27], v[160:163], v[202:205], v[24:27]
	v_mfma_f32_16x16x32_bf16 v[12:15], v[144:147], v[210:213], v[12:15]
	v_mfma_f32_16x16x32_bf16 v[8:11], v[160:163], v[210:213], v[8:11]
	v_mfma_f32_16x16x32_bf16 v[60:63], v[148:151], v[190:193], v[60:63]
	v_mfma_f32_16x16x32_bf16 v[56:59], v[164:167], v[190:193], v[56:59]
	v_mfma_f32_16x16x32_bf16 v[44:47], v[148:151], v[198:201], v[44:47]
	v_mfma_f32_16x16x32_bf16 v[40:43], v[164:167], v[198:201], v[40:43]
	v_mfma_f32_16x16x32_bf16 v[28:31], v[148:151], v[206:209], v[28:31]
	v_mfma_f32_16x16x32_bf16 v[24:27], v[164:167], v[206:209], v[24:27]
	v_mfma_f32_16x16x32_bf16 v[12:15], v[148:151], v[214:217], v[12:15]
	v_mfma_f32_16x16x32_bf16 v[8:11], v[164:167], v[214:217], v[8:11]
	s_setprio 0
	s_setprio 1
	v_mfma_f32_16x16x32_bf16 v[52:55], v[168:171], v[186:189], v[52:55]
	v_mfma_f32_16x16x32_bf16 v[48:51], v[176:179], v[186:189], v[48:51]
	v_mfma_f32_16x16x32_bf16 v[36:39], v[168:171], v[194:197], v[36:39]
	v_mfma_f32_16x16x32_bf16 v[32:35], v[176:179], v[194:197], v[32:35]
	v_mfma_f32_16x16x32_bf16 v[20:23], v[168:171], v[202:205], v[20:23]
	v_mfma_f32_16x16x32_bf16 v[16:19], v[176:179], v[202:205], v[16:19]
	v_mfma_f32_16x16x32_bf16 v[4:7], v[168:171], v[210:213], v[4:7]
	v_mfma_f32_16x16x32_bf16 v[0:3], v[176:179], v[210:213], v[0:3]
	v_mfma_f32_16x16x32_bf16 v[52:55], v[172:175], v[190:193], v[52:55]
	v_mfma_f32_16x16x32_bf16 v[48:51], v[182:185], v[190:193], v[48:51]
	v_mfma_f32_16x16x32_bf16 v[36:39], v[172:175], v[198:201], v[36:39]
	v_mfma_f32_16x16x32_bf16 v[32:35], v[182:185], v[198:201], v[32:35]
	v_mfma_f32_16x16x32_bf16 v[20:23], v[172:175], v[206:209], v[20:23]
	v_mfma_f32_16x16x32_bf16 v[16:19], v[182:185], v[206:209], v[16:19]
	v_mfma_f32_16x16x32_bf16 v[4:7], v[172:175], v[214:217], v[4:7]
	v_mfma_f32_16x16x32_bf16 v[0:3], v[182:185], v[214:217], v[0:3]
	s_setprio 0
	s_barrier
	s_add_i32 s66, 0, 0x18000
	v_add_u32_e32 v159, s66, v154
	s_add_i32 s67, 0, 0x1c000
	ds_read_b128 v[144:147], v159
	ds_read_b128 v[148:151], v159 offset:1024
	ds_read_b128 v[160:163], v159 offset:2048
	ds_read_b128 v[164:167], v159 offset:3072
	v_add_u32_e32 v159, s67, v154
	ds_read_b128 v[168:171], v159
	ds_read_b128 v[172:175], v159 offset:1024
	ds_read_b128 v[176:179], v159 offset:2048
	ds_read_b128 v[182:185], v159 offset:3072
	s_add_u32 s36, s36, 0x40000
	s_addc_u32 s37, s37, 0
	s_mov_b32 m0, s45
	v_lshl_add_u64 v[224:225], s[36:37], 0, v[134:135]
	ds_read_b128 v[186:189], v157 offset:32768
	ds_read_b128 v[190:193], v157 offset:33792
	ds_read_b128 v[194:197], v157 offset:34816
	ds_read_b128 v[198:201], v157 offset:35840
	ds_read_b128 v[202:205], v157 offset:36864
	ds_read_b128 v[206:209], v157 offset:37888
	ds_read_b128 v[210:213], v157 offset:38912
	ds_read_b128 v[214:217], v157 offset:39936
	global_load_lds_dwordx4 v[224:225], off
	v_lshl_add_u64 v[224:225], s[36:37], 0, v[130:131]
	s_mov_b32 m0, s48
	s_nop 0
	global_load_lds_dwordx4 v[224:225], off
	s_waitcnt vmcnt(8)
	s_waitcnt lgkmcnt(0)
	s_barrier
	s_setprio 1
	s_waitcnt lgkmcnt(0)
	v_mfma_f32_16x16x32_bf16 v[124:127], v[144:147], v[186:189], v[124:127]
	v_mfma_f32_16x16x32_bf16 v[120:123], v[160:163], v[186:189], v[120:123]
	v_mfma_f32_16x16x32_bf16 v[108:111], v[144:147], v[194:197], v[108:111]
	v_mfma_f32_16x16x32_bf16 v[104:107], v[160:163], v[194:197], v[104:107]
	v_mfma_f32_16x16x32_bf16 v[92:95], v[144:147], v[202:205], v[92:95]
	v_mfma_f32_16x16x32_bf16 v[88:91], v[160:163], v[202:205], v[88:91]
	v_mfma_f32_16x16x32_bf16 v[76:79], v[144:147], v[210:213], v[76:79]
	v_mfma_f32_16x16x32_bf16 v[72:75], v[160:163], v[210:213], v[72:75]
	v_mfma_f32_16x16x32_bf16 v[124:127], v[148:151], v[190:193], v[124:127]
	v_mfma_f32_16x16x32_bf16 v[120:123], v[164:167], v[190:193], v[120:123]
	v_mfma_f32_16x16x32_bf16 v[108:111], v[148:151], v[198:201], v[108:111]
	v_mfma_f32_16x16x32_bf16 v[104:107], v[164:167], v[198:201], v[104:107]
	v_mfma_f32_16x16x32_bf16 v[92:95], v[148:151], v[206:209], v[92:95]
	v_mfma_f32_16x16x32_bf16 v[88:91], v[164:167], v[206:209], v[88:91]
	v_mfma_f32_16x16x32_bf16 v[76:79], v[148:151], v[214:217], v[76:79]
	v_mfma_f32_16x16x32_bf16 v[72:75], v[164:167], v[214:217], v[72:75]
	s_setprio 0
	s_setprio 1
	v_mfma_f32_16x16x32_bf16 v[116:119], v[168:171], v[186:189], v[116:119]
	v_mfma_f32_16x16x32_bf16 v[112:115], v[176:179], v[186:189], v[112:115]
	v_mfma_f32_16x16x32_bf16 v[100:103], v[168:171], v[194:197], v[100:103]
	v_mfma_f32_16x16x32_bf16 v[96:99], v[176:179], v[194:197], v[96:99]
	v_mfma_f32_16x16x32_bf16 v[84:87], v[168:171], v[202:205], v[84:87]
	v_mfma_f32_16x16x32_bf16 v[80:83], v[176:179], v[202:205], v[80:83]
	v_mfma_f32_16x16x32_bf16 v[68:71], v[168:171], v[210:213], v[68:71]
	v_mfma_f32_16x16x32_bf16 v[64:67], v[176:179], v[210:213], v[64:67]
	v_mfma_f32_16x16x32_bf16 v[116:119], v[172:175], v[190:193], v[116:119]
	v_mfma_f32_16x16x32_bf16 v[112:115], v[182:185], v[190:193], v[112:115]
	v_mfma_f32_16x16x32_bf16 v[100:103], v[172:175], v[198:201], v[100:103]
	v_mfma_f32_16x16x32_bf16 v[96:99], v[182:185], v[198:201], v[96:99]
	v_mfma_f32_16x16x32_bf16 v[84:87], v[172:175], v[206:209], v[84:87]
	v_mfma_f32_16x16x32_bf16 v[80:83], v[182:185], v[206:209], v[80:83]
	v_mfma_f32_16x16x32_bf16 v[68:71], v[172:175], v[214:217], v[68:71]
	v_mfma_f32_16x16x32_bf16 v[64:67], v[182:185], v[214:217], v[64:67]
	s_setprio 0
	s_barrier
	s_add_i32 s36, s66, s42
	v_lshl_add_u64 v[152:153], v[152:153], 0, s[18:19]
	s_mov_b32 m0, s36
	ds_read_b128 v[186:189], v157 offset:49152
	ds_read_b128 v[190:193], v157 offset:50176
	ds_read_b128 v[194:197], v157 offset:51200
	ds_read_b128 v[198:201], v157 offset:52224
	ds_read_b128 v[202:205], v157 offset:53248
	ds_read_b128 v[206:209], v157 offset:54272
	ds_read_b128 v[210:213], v157 offset:55296
	ds_read_b128 v[214:217], v157 offset:56320
	global_load_lds_dwordx4 v[152:153], off
	s_add_i32 m0, s36, 0x2000
	s_add_u32 s34, s34, 0x40080
	v_lshl_add_u64 v[152:153], v[218:219], 0, s[18:19]
	s_addc_u32 s35, s35, 0
	s_add_i32 s36, s67, s42
	global_load_lds_dwordx4 v[152:153], off
	v_lshl_add_u64 v[152:153], s[34:35], 0, v[132:133]
	s_mov_b32 m0, s36
	s_nop 0
	global_load_lds_dwordx4 v[152:153], off
	v_lshl_add_u64 v[152:153], s[34:35], 0, v[128:129]
	s_add_i32 m0, s36, 0x2000
	s_nop 0
	global_load_lds_dwordx4 v[152:153], off
	v_lshl_add_u64 v[152:153], v[220:221], 0, s[18:19]
	s_mov_b32 m0, s52
	s_nop 0
	global_load_lds_dwordx4 v[152:153], off
	v_lshl_add_u64 v[152:153], v[222:223], 0, s[18:19]
	s_mov_b32 m0, s53
	s_nop 0
	global_load_lds_dwordx4 v[152:153], off
	s_waitcnt vmcnt(8)
	s_waitcnt lgkmcnt(0)
	s_barrier
	s_setprio 1
	s_waitcnt lgkmcnt(0)
	v_mfma_f32_16x16x32_bf16 v[60:63], v[144:147], v[186:189], v[60:63]
	v_mfma_f32_16x16x32_bf16 v[56:59], v[160:163], v[186:189], v[56:59]
	v_mfma_f32_16x16x32_bf16 v[44:47], v[144:147], v[194:197], v[44:47]
	v_mfma_f32_16x16x32_bf16 v[40:43], v[160:163], v[194:197], v[40:43]
	v_mfma_f32_16x16x32_bf16 v[28:31], v[144:147], v[202:205], v[28:31]
	v_mfma_f32_16x16x32_bf16 v[24:27], v[160:163], v[202:205], v[24:27]
	v_mfma_f32_16x16x32_bf16 v[12:15], v[144:147], v[210:213], v[12:15]
	v_mfma_f32_16x16x32_bf16 v[8:11], v[160:163], v[210:213], v[8:11]
	v_mfma_f32_16x16x32_bf16 v[60:63], v[148:151], v[190:193], v[60:63]
	v_mfma_f32_16x16x32_bf16 v[56:59], v[164:167], v[190:193], v[56:59]
	v_mfma_f32_16x16x32_bf16 v[44:47], v[148:151], v[198:201], v[44:47]
	v_mfma_f32_16x16x32_bf16 v[40:43], v[164:167], v[198:201], v[40:43]
	v_mfma_f32_16x16x32_bf16 v[28:31], v[148:151], v[206:209], v[28:31]
	v_mfma_f32_16x16x32_bf16 v[24:27], v[164:167], v[206:209], v[24:27]
	v_mfma_f32_16x16x32_bf16 v[12:15], v[148:151], v[214:217], v[12:15]
	v_mfma_f32_16x16x32_bf16 v[8:11], v[164:167], v[214:217], v[8:11]
	s_setprio 0
	s_setprio 1
	v_mfma_f32_16x16x32_bf16 v[52:55], v[168:171], v[186:189], v[52:55]
	v_mfma_f32_16x16x32_bf16 v[48:51], v[176:179], v[186:189], v[48:51]
	v_mfma_f32_16x16x32_bf16 v[36:39], v[168:171], v[194:197], v[36:39]
	v_mfma_f32_16x16x32_bf16 v[32:35], v[176:179], v[194:197], v[32:35]
	v_mfma_f32_16x16x32_bf16 v[20:23], v[168:171], v[202:205], v[20:23]
	v_mfma_f32_16x16x32_bf16 v[16:19], v[176:179], v[202:205], v[16:19]
	v_mfma_f32_16x16x32_bf16 v[4:7], v[168:171], v[210:213], v[4:7]
	v_mfma_f32_16x16x32_bf16 v[0:3], v[176:179], v[210:213], v[0:3]
	v_mfma_f32_16x16x32_bf16 v[52:55], v[172:175], v[190:193], v[52:55]
	v_mfma_f32_16x16x32_bf16 v[48:51], v[182:185], v[190:193], v[48:51]
	v_mfma_f32_16x16x32_bf16 v[36:39], v[172:175], v[198:201], v[36:39]
	v_mfma_f32_16x16x32_bf16 v[32:35], v[182:185], v[198:201], v[32:35]
	v_mfma_f32_16x16x32_bf16 v[20:23], v[172:175], v[206:209], v[20:23]
	v_mfma_f32_16x16x32_bf16 v[16:19], v[182:185], v[206:209], v[16:19]
	v_mfma_f32_16x16x32_bf16 v[4:7], v[172:175], v[214:217], v[4:7]
	v_mfma_f32_16x16x32_bf16 v[0:3], v[182:185], v[214:217], v[0:3]
	s_setprio 0
	s_add_i32 s65, s65, 2
	s_add_u32 s30, s30, 0x100
	s_addc_u32 s31, s31, 0
	s_add_u32 s63, s63, 0x100
	s_addc_u32 s64, s64, 0
	s_cmp_gt_u32 s65, 13
	s_barrier
	s_cbranch_scc0 .LBB0_1482
	s_and_b64 vcc, exec, s[20:21]
	s_cbranch_vccz .LBB0_1485
	s_barrier

.Lmm_8_7:
	s_setprio 0
	s_add_i32 s58, s58, 2
	s_add_u32 s56, s56, 0x100
	s_addc_u32 s57, s57, 0
	s_cmp_gt_u32 s58, 41
	s_mov_b64 s[24:25], s[26:27]
	s_barrier
	s_cbranch_scc0 .Lqk_8
	s_branch .Lqk_join_8

.LBB0_1518:
	ds_read_b128 v[140:143], v182
	ds_read_b128 v[144:147], v182 offset:1024
	ds_read_b128 v[148:151], v182 offset:2048
	ds_read_b128 v[152:155], v182 offset:3072
	ds_read_b128 v[156:159], v183
	ds_read_b128 v[160:163], v183 offset:1024
	ds_read_b128 v[164:167], v183 offset:2048
	ds_read_b128 v[168:171], v183 offset:3072
	s_add_u32 s26, s24, 0x100
	s_addc_u32 s27, s25, 0
	s_cmp_eq_u32 s58, 40
	s_cselect_b32 s31, s9, s27
	s_cselect_b32 s30, s8, s26
	s_cselect_b32 s29, s23, s57
	s_cselect_b32 s28, s22, s56
	v_lshl_add_u64 v[210:211], s[24:25], 0, v[132:133]
	s_add_i32 m0, s39, 0xc000
	ds_read_b128 v[172:175], v184
	ds_read_b128 v[176:179], v184 offset:1024
	ds_read_b128 v[186:189], v184 offset:2048
	ds_read_b128 v[190:193], v184 offset:3072
	ds_read_b128 v[194:197], v184 offset:4096
	ds_read_b128 v[198:201], v184 offset:5120
	ds_read_b128 v[202:205], v184 offset:6144
	ds_read_b128 v[206:209], v184 offset:7168
	global_load_lds_dwordx4 v[210:211], off
	v_lshl_add_u64 v[210:211], s[24:25], 0, v[134:135]
	s_add_i32 m0, s39, 0xe000
	s_nop 0
	global_load_lds_dwordx4 v[210:211], off
	s_waitcnt vmcnt(8)
	s_waitcnt lgkmcnt(0)
	s_barrier
	s_setprio 1
	s_waitcnt lgkmcnt(0)
	v_mfma_f32_16x16x32_bf16 v[124:127], v[140:143], v[172:175], v[124:127]
	v_mfma_f32_16x16x32_bf16 v[120:123], v[148:151], v[172:175], v[120:123]
	v_mfma_f32_16x16x32_bf16 v[108:111], v[140:143], v[186:189], v[108:111]
	v_mfma_f32_16x16x32_bf16 v[104:107], v[148:151], v[186:189], v[104:107]
	v_mfma_f32_16x16x32_bf16 v[92:95], v[140:143], v[194:197], v[92:95]
	v_mfma_f32_16x16x32_bf16 v[88:91], v[148:151], v[194:197], v[88:91]
	v_mfma_f32_16x16x32_bf16 v[76:79], v[140:143], v[202:205], v[76:79]
	v_mfma_f32_16x16x32_bf16 v[72:75], v[148:151], v[202:205], v[72:75]
	v_mfma_f32_16x16x32_bf16 v[124:127], v[144:147], v[176:179], v[124:127]
	v_mfma_f32_16x16x32_bf16 v[120:123], v[152:155], v[176:179], v[120:123]
	v_mfma_f32_16x16x32_bf16 v[108:111], v[144:147], v[190:193], v[108:111]
	v_mfma_f32_16x16x32_bf16 v[104:107], v[152:155], v[190:193], v[104:107]
	v_mfma_f32_16x16x32_bf16 v[92:95], v[144:147], v[198:201], v[92:95]
	v_mfma_f32_16x16x32_bf16 v[88:91], v[152:155], v[198:201], v[88:91]
	v_mfma_f32_16x16x32_bf16 v[76:79], v[144:147], v[206:209], v[76:79]
	v_mfma_f32_16x16x32_bf16 v[72:75], v[152:155], v[206:209], v[72:75]
	s_setprio 0
	s_setprio 1
	v_mfma_f32_16x16x32_bf16 v[116:119], v[156:159], v[172:175], v[116:119]
	v_mfma_f32_16x16x32_bf16 v[112:115], v[164:167], v[172:175], v[112:115]
	v_mfma_f32_16x16x32_bf16 v[100:103], v[156:159], v[186:189], v[100:103]
	v_mfma_f32_16x16x32_bf16 v[96:99], v[164:167], v[186:189], v[96:99]
	v_mfma_f32_16x16x32_bf16 v[84:87], v[156:159], v[194:197], v[84:87]
	v_mfma_f32_16x16x32_bf16 v[80:83], v[164:167], v[194:197], v[80:83]
	v_mfma_f32_16x16x32_bf16 v[68:71], v[156:159], v[202:205], v[68:71]
	v_mfma_f32_16x16x32_bf16 v[64:67], v[164:167], v[202:205], v[64:67]
	v_mfma_f32_16x16x32_bf16 v[116:119], v[160:163], v[176:179], v[116:119]
	v_mfma_f32_16x16x32_bf16 v[112:115], v[168:171], v[176:179], v[112:115]
	v_mfma_f32_16x16x32_bf16 v[100:103], v[160:163], v[190:193], v[100:103]
	v_mfma_f32_16x16x32_bf16 v[96:99], v[168:171], v[190:193], v[96:99]
	v_mfma_f32_16x16x32_bf16 v[84:87], v[160:163], v[198:201], v[84:87]
	v_mfma_f32_16x16x32_bf16 v[80:83], v[168:171], v[198:201], v[80:83]
	v_mfma_f32_16x16x32_bf16 v[68:71], v[160:163], v[206:209], v[68:71]
	v_mfma_f32_16x16x32_bf16 v[64:67], v[168:171], v[206:209], v[64:67]
	s_setprio 0
	s_barrier
	s_add_i32 s24, s50, s38
	v_lshl_add_u64 v[210:211], s[28:29], 0, v[128:129]
	s_mov_b32 m0, s24
	ds_read_b128 v[172:175], v184 offset:16384
	ds_read_b128 v[176:179], v184 offset:17408
	ds_read_b128 v[186:189], v184 offset:18432
	ds_read_b128 v[190:193], v184 offset:19456
	ds_read_b128 v[194:197], v184 offset:20480
	ds_read_b128 v[198:201], v184 offset:21504
	ds_read_b128 v[202:205], v184 offset:22528
	ds_read_b128 v[206:209], v184 offset:23552
	global_load_lds_dwordx4 v[210:211], off
	s_add_i32 m0, s24, 0x2000
	s_add_u32 s24, s28, 0xb0000
	v_lshl_add_u64 v[212:213], s[28:29], 0, v[130:131]
	s_addc_u32 s25, s29, 0
	s_add_i32 s59, s51, s38
	global_load_lds_dwordx4 v[212:213], off
	v_lshl_add_u64 v[214:215], s[24:25], 0, v[128:129]
	s_mov_b32 m0, s59
	v_lshl_add_u64 v[216:217], s[30:31], 0, v[130:131]
	global_load_lds_dwordx4 v[214:215], off
	v_lshl_add_u64 v[214:215], s[24:25], 0, v[130:131]
	s_add_i32 m0, s59, 0x2000
	s_nop 0
	global_load_lds_dwordx4 v[214:215], off
	v_lshl_add_u64 v[214:215], s[30:31], 0, v[128:129]
	s_mov_b32 m0, s39
	s_nop 0
	global_load_lds_dwordx4 v[214:215], off
	s_mov_b32 m0, s40
	s_nop 0
	global_load_lds_dwordx4 v[216:217], off
	s_waitcnt vmcnt(8)
	s_waitcnt lgkmcnt(0)
	s_barrier
	s_setprio 1
	s_waitcnt lgkmcnt(0)
	v_mfma_f32_16x16x32_bf16 v[60:63], v[140:143], v[172:175], v[60:63]
	v_mfma_f32_16x16x32_bf16 v[56:59], v[148:151], v[172:175], v[56:59]
	v_mfma_f32_16x16x32_bf16 v[44:47], v[140:143], v[186:189], v[44:47]
	v_mfma_f32_16x16x32_bf16 v[40:43], v[148:151], v[186:189], v[40:43]
	v_mfma_f32_16x16x32_bf16 v[28:31], v[140:143], v[194:197], v[28:31]
	v_mfma_f32_16x16x32_bf16 v[24:27], v[148:151], v[194:197], v[24:27]
	v_mfma_f32_16x16x32_bf16 v[12:15], v[140:143], v[202:205], v[12:15]
	v_mfma_f32_16x16x32_bf16 v[8:11], v[148:151], v[202:205], v[8:11]
	v_mfma_f32_16x16x32_bf16 v[60:63], v[144:147], v[176:179], v[60:63]
	v_mfma_f32_16x16x32_bf16 v[56:59], v[152:155], v[176:179], v[56:59]
	v_mfma_f32_16x16x32_bf16 v[44:47], v[144:147], v[190:193], v[44:47]
	v_mfma_f32_16x16x32_bf16 v[40:43], v[152:155], v[190:193], v[40:43]
	v_mfma_f32_16x16x32_bf16 v[28:31], v[144:147], v[198:201], v[28:31]
	v_mfma_f32_16x16x32_bf16 v[24:27], v[152:155], v[198:201], v[24:27]
	v_mfma_f32_16x16x32_bf16 v[12:15], v[144:147], v[206:209], v[12:15]
	v_mfma_f32_16x16x32_bf16 v[8:11], v[152:155], v[206:209], v[8:11]
	s_setprio 0
	s_setprio 1
	v_mfma_f32_16x16x32_bf16 v[52:55], v[156:159], v[172:175], v[52:55]
	v_mfma_f32_16x16x32_bf16 v[48:51], v[164:167], v[172:175], v[48:51]
	v_mfma_f32_16x16x32_bf16 v[36:39], v[156:159], v[186:189], v[36:39]
	v_mfma_f32_16x16x32_bf16 v[32:35], v[164:167], v[186:189], v[32:35]
	v_mfma_f32_16x16x32_bf16 v[20:23], v[156:159], v[194:197], v[20:23]
	v_mfma_f32_16x16x32_bf16 v[16:19], v[164:167], v[194:197], v[16:19]
	v_mfma_f32_16x16x32_bf16 v[4:7], v[156:159], v[202:205], v[4:7]
	v_mfma_f32_16x16x32_bf16 v[0:3], v[164:167], v[202:205], v[0:3]
	v_mfma_f32_16x16x32_bf16 v[52:55], v[160:163], v[176:179], v[52:55]
	v_mfma_f32_16x16x32_bf16 v[48:51], v[168:171], v[176:179], v[48:51]
	v_mfma_f32_16x16x32_bf16 v[36:39], v[160:163], v[190:193], v[36:39]
	v_mfma_f32_16x16x32_bf16 v[32:35], v[168:171], v[190:193], v[32:35]
	v_mfma_f32_16x16x32_bf16 v[20:23], v[160:163], v[198:201], v[20:23]
	v_mfma_f32_16x16x32_bf16 v[16:19], v[168:171], v[198:201], v[16:19]
	v_mfma_f32_16x16x32_bf16 v[4:7], v[160:163], v[206:209], v[4:7]
	v_mfma_f32_16x16x32_bf16 v[0:3], v[168:171], v[206:209], v[0:3]
	s_setprio 0
	s_barrier
	s_add_i32 s59, 0, 0x18000
	s_add_i32 s63, 0, 0x1c000
	v_add_u32_e32 v152, s59, v181
	v_add_u32_e32 v168, s63, v181
	ds_read_b128 v[140:143], v152
	ds_read_b128 v[144:147], v152 offset:1024
	ds_read_b128 v[148:151], v152 offset:2048
	ds_read_b128 v[152:155], v152 offset:3072
	ds_read_b128 v[156:159], v168
	ds_read_b128 v[160:163], v168 offset:1024
	ds_read_b128 v[164:167], v168 offset:2048
	ds_read_b128 v[168:171], v168 offset:3072
	s_add_u32 s24, s30, 0xb0000
	s_addc_u32 s25, s31, 0
	s_mov_b32 m0, s41
	v_lshl_add_u64 v[218:219], s[24:25], 0, v[128:129]
	ds_read_b128 v[172:175], v184 offset:32768
	ds_read_b128 v[176:179], v184 offset:33792
	ds_read_b128 v[186:189], v184 offset:34816
	ds_read_b128 v[190:193], v184 offset:35840
	ds_read_b128 v[194:197], v184 offset:36864
	ds_read_b128 v[198:201], v184 offset:37888
	ds_read_b128 v[202:205], v184 offset:38912
	ds_read_b128 v[206:209], v184 offset:39936
	global_load_lds_dwordx4 v[218:219], off
	v_lshl_add_u64 v[218:219], s[24:25], 0, v[130:131]
	s_mov_b32 m0, s42
	s_nop 0
	global_load_lds_dwordx4 v[218:219], off
	s_waitcnt vmcnt(8)
	s_waitcnt lgkmcnt(0)
	s_barrier
	s_setprio 1
	s_waitcnt lgkmcnt(0)
	v_mfma_f32_16x16x32_bf16 v[124:127], v[140:143], v[172:175], v[124:127]
	v_mfma_f32_16x16x32_bf16 v[120:123], v[148:151], v[172:175], v[120:123]
	v_mfma_f32_16x16x32_bf16 v[108:111], v[140:143], v[186:189], v[108:111]
	v_mfma_f32_16x16x32_bf16 v[104:107], v[148:151], v[186:189], v[104:107]
	v_mfma_f32_16x16x32_bf16 v[92:95], v[140:143], v[194:197], v[92:95]
	v_mfma_f32_16x16x32_bf16 v[88:91], v[148:151], v[194:197], v[88:91]
	v_mfma_f32_16x16x32_bf16 v[76:79], v[140:143], v[202:205], v[76:79]
	v_mfma_f32_16x16x32_bf16 v[72:75], v[148:151], v[202:205], v[72:75]
	v_mfma_f32_16x16x32_bf16 v[124:127], v[144:147], v[176:179], v[124:127]
	v_mfma_f32_16x16x32_bf16 v[120:123], v[152:155], v[176:179], v[120:123]
	v_mfma_f32_16x16x32_bf16 v[108:111], v[144:147], v[190:193], v[108:111]
	v_mfma_f32_16x16x32_bf16 v[104:107], v[152:155], v[190:193], v[104:107]
	v_mfma_f32_16x16x32_bf16 v[92:95], v[144:147], v[198:201], v[92:95]
	v_mfma_f32_16x16x32_bf16 v[88:91], v[152:155], v[198:201], v[88:91]
	v_mfma_f32_16x16x32_bf16 v[76:79], v[144:147], v[206:209], v[76:79]
	v_mfma_f32_16x16x32_bf16 v[72:75], v[152:155], v[206:209], v[72:75]
	s_setprio 0
	s_setprio 1
	v_mfma_f32_16x16x32_bf16 v[116:119], v[156:159], v[172:175], v[116:119]
	v_mfma_f32_16x16x32_bf16 v[112:115], v[164:167], v[172:175], v[112:115]
	v_mfma_f32_16x16x32_bf16 v[100:103], v[156:159], v[186:189], v[100:103]
	v_mfma_f32_16x16x32_bf16 v[96:99], v[164:167], v[186:189], v[96:99]
	v_mfma_f32_16x16x32_bf16 v[84:87], v[156:159], v[194:197], v[84:87]
	v_mfma_f32_16x16x32_bf16 v[80:83], v[164:167], v[194:197], v[80:83]
	v_mfma_f32_16x16x32_bf16 v[68:71], v[156:159], v[202:205], v[68:71]
	v_mfma_f32_16x16x32_bf16 v[64:67], v[164:167], v[202:205], v[64:67]
	v_mfma_f32_16x16x32_bf16 v[116:119], v[160:163], v[176:179], v[116:119]
	v_mfma_f32_16x16x32_bf16 v[112:115], v[168:171], v[176:179], v[112:115]
	v_mfma_f32_16x16x32_bf16 v[100:103], v[160:163], v[190:193], v[100:103]
	v_mfma_f32_16x16x32_bf16 v[96:99], v[168:171], v[190:193], v[96:99]
	v_mfma_f32_16x16x32_bf16 v[84:87], v[160:163], v[198:201], v[84:87]
	v_mfma_f32_16x16x32_bf16 v[80:83], v[168:171], v[198:201], v[80:83]
	v_mfma_f32_16x16x32_bf16 v[68:71], v[160:163], v[206:209], v[68:71]
	v_mfma_f32_16x16x32_bf16 v[64:67], v[168:171], v[206:209], v[64:67]
	s_setprio 0
	s_barrier
	s_add_i32 s24, s59, s38
	v_lshl_add_u64 v[210:211], v[210:211], 0, s[18:19]
	s_mov_b32 m0, s24
	ds_read_b128 v[172:175], v184 offset:49152
	ds_read_b128 v[176:179], v184 offset:50176
	ds_read_b128 v[186:189], v184 offset:51200
	ds_read_b128 v[190:193], v184 offset:52224
	ds_read_b128 v[194:197], v184 offset:53248
	ds_read_b128 v[198:201], v184 offset:54272
	ds_read_b128 v[202:205], v184 offset:55296
	ds_read_b128 v[206:209], v184 offset:56320
	global_load_lds_dwordx4 v[210:211], off
	s_add_i32 m0, s24, 0x2000
	s_add_u32 s24, s28, 0xb0080
	v_lshl_add_u64 v[210:211], v[212:213], 0, s[18:19]
	s_addc_u32 s25, s29, 0
	s_add_i32 s28, s63, s38
	global_load_lds_dwordx4 v[210:211], off
	v_lshl_add_u64 v[210:211], s[24:25], 0, v[128:129]
	s_mov_b32 m0, s28
	s_nop 0
	global_load_lds_dwordx4 v[210:211], off
	v_lshl_add_u64 v[210:211], s[24:25], 0, v[130:131]
	s_add_i32 m0, s28, 0x2000
	s_nop 0
	global_load_lds_dwordx4 v[210:211], off
	v_lshl_add_u64 v[210:211], v[214:215], 0, s[18:19]
	s_mov_b32 m0, s48
	s_nop 0
	global_load_lds_dwordx4 v[210:211], off
	v_lshl_add_u64 v[210:211], v[216:217], 0, s[18:19]
	s_mov_b32 m0, s49
	s_nop 0
	global_load_lds_dwordx4 v[210:211], off
	s_waitcnt vmcnt(8)
	s_waitcnt lgkmcnt(0)
	s_barrier
	s_setprio 1
	s_waitcnt lgkmcnt(0)
	v_mfma_f32_16x16x32_bf16 v[60:63], v[140:143], v[172:175], v[60:63]
	v_mfma_f32_16x16x32_bf16 v[56:59], v[148:151], v[172:175], v[56:59]
	v_mfma_f32_16x16x32_bf16 v[44:47], v[140:143], v[186:189], v[44:47]
	v_mfma_f32_16x16x32_bf16 v[40:43], v[148:151], v[186:189], v[40:43]
	v_mfma_f32_16x16x32_bf16 v[28:31], v[140:143], v[194:197], v[28:31]
	v_mfma_f32_16x16x32_bf16 v[24:27], v[148:151], v[194:197], v[24:27]
	v_mfma_f32_16x16x32_bf16 v[12:15], v[140:143], v[202:205], v[12:15]
	v_mfma_f32_16x16x32_bf16 v[8:11], v[148:151], v[202:205], v[8:11]
	v_mfma_f32_16x16x32_bf16 v[60:63], v[144:147], v[176:179], v[60:63]
	v_mfma_f32_16x16x32_bf16 v[56:59], v[152:155], v[176:179], v[56:59]
	v_mfma_f32_16x16x32_bf16 v[44:47], v[144:147], v[190:193], v[44:47]
	v_mfma_f32_16x16x32_bf16 v[40:43], v[152:155], v[190:193], v[40:43]
	v_mfma_f32_16x16x32_bf16 v[28:31], v[144:147], v[198:201], v[28:31]
	v_mfma_f32_16x16x32_bf16 v[24:27], v[152:155], v[198:201], v[24:27]
	v_mfma_f32_16x16x32_bf16 v[12:15], v[144:147], v[206:209], v[12:15]
	v_mfma_f32_16x16x32_bf16 v[8:11], v[152:155], v[206:209], v[8:11]
	s_setprio 0
	s_setprio 1
	v_mfma_f32_16x16x32_bf16 v[52:55], v[156:159], v[172:175], v[52:55]
	v_mfma_f32_16x16x32_bf16 v[48:51], v[164:167], v[172:175], v[48:51]
	v_mfma_f32_16x16x32_bf16 v[36:39], v[156:159], v[186:189], v[36:39]
	v_mfma_f32_16x16x32_bf16 v[32:35], v[164:167], v[186:189], v[32:35]
	v_mfma_f32_16x16x32_bf16 v[20:23], v[156:159], v[194:197], v[20:23]
	v_mfma_f32_16x16x32_bf16 v[16:19], v[164:167], v[194:197], v[16:19]
	v_mfma_f32_16x16x32_bf16 v[4:7], v[156:159], v[202:205], v[4:7]
	v_mfma_f32_16x16x32_bf16 v[0:3], v[164:167], v[202:205], v[0:3]
	v_mfma_f32_16x16x32_bf16 v[52:55], v[160:163], v[176:179], v[52:55]
	v_mfma_f32_16x16x32_bf16 v[48:51], v[168:171], v[176:179], v[48:51]
	v_mfma_f32_16x16x32_bf16 v[36:39], v[160:163], v[190:193], v[36:39]
	v_mfma_f32_16x16x32_bf16 v[32:35], v[168:171], v[190:193], v[32:35]
	v_mfma_f32_16x16x32_bf16 v[20:23], v[160:163], v[198:201], v[20:23]
	v_mfma_f32_16x16x32_bf16 v[16:19], v[168:171], v[198:201], v[16:19]
	v_mfma_f32_16x16x32_bf16 v[4:7], v[160:163], v[206:209], v[4:7]
	v_mfma_f32_16x16x32_bf16 v[0:3], v[168:171], v[206:209], v[0:3]
	s_setprio 0
	s_add_i32 s58, s58, 2
	s_add_u32 s56, s56, 0x100
	s_addc_u32 s57, s57, 0
	s_cmp_gt_u32 s58, 41
	s_mov_b64 s[24:25], s[26:27]
	s_barrier
	s_cbranch_scc0 .LBB0_1518

.LBB0_1566:
	ds_read_b128 v[128:131], v175
	ds_read_b128 v[132:135], v175 offset:1024
	ds_read_b128 v[154:157], v175 offset:2048
	ds_read_b128 v[158:161], v175 offset:3072
	ds_read_b128 v[162:165], v176
	ds_read_b128 v[166:169], v176 offset:1024
	ds_read_b128 v[170:173], v176 offset:2048
	ds_read_b128 v[182:185], v176 offset:3072
	s_add_u32 s10, s8, 0xfffc0080
	s_addc_u32 s11, s9, -1
	s_cmp_eq_u32 s44, 12
	s_cselect_b32 s13, s1, s11
	s_cselect_b32 s12, s35, s10
	s_cselect_b32 s11, s31, s43
	s_cselect_b32 s10, s41, s42
	v_lshl_add_u64 v[218:219], s[8:9], 0, v[146:147]
	s_add_i32 m0, s55, 0xc000
	ds_read_b128 v[186:189], v177
	ds_read_b128 v[190:193], v177 offset:1024
	ds_read_b128 v[194:197], v177 offset:2048
	ds_read_b128 v[198:201], v177 offset:3072
	ds_read_b128 v[202:205], v177 offset:4096
	ds_read_b128 v[206:209], v177 offset:5120
	ds_read_b128 v[210:213], v177 offset:6144
	ds_read_b128 v[214:217], v177 offset:7168
	global_load_lds_dwordx4 v[218:219], off
	v_lshl_add_u64 v[218:219], s[8:9], 0, v[148:149]
	s_add_i32 m0, s55, 0xe000
	s_nop 0
	global_load_lds_dwordx4 v[218:219], off
	s_waitcnt vmcnt(8)
	s_waitcnt lgkmcnt(0)
	s_barrier
	s_setprio 1
	s_waitcnt lgkmcnt(0)
	v_mfma_f32_16x16x32_bf16 v[124:127], v[128:131], v[186:189], v[124:127]
	v_mfma_f32_16x16x32_bf16 v[120:123], v[154:157], v[186:189], v[120:123]
	v_mfma_f32_16x16x32_bf16 v[108:111], v[128:131], v[194:197], v[108:111]
	v_mfma_f32_16x16x32_bf16 v[104:107], v[154:157], v[194:197], v[104:107]
	v_mfma_f32_16x16x32_bf16 v[92:95], v[128:131], v[202:205], v[92:95]
	v_mfma_f32_16x16x32_bf16 v[88:91], v[154:157], v[202:205], v[88:91]
	v_mfma_f32_16x16x32_bf16 v[76:79], v[128:131], v[210:213], v[76:79]
	v_mfma_f32_16x16x32_bf16 v[72:75], v[154:157], v[210:213], v[72:75]
	v_mfma_f32_16x16x32_bf16 v[124:127], v[132:135], v[190:193], v[124:127]
	v_mfma_f32_16x16x32_bf16 v[120:123], v[158:161], v[190:193], v[120:123]
	v_mfma_f32_16x16x32_bf16 v[108:111], v[132:135], v[198:201], v[108:111]
	v_mfma_f32_16x16x32_bf16 v[104:107], v[158:161], v[198:201], v[104:107]
	v_mfma_f32_16x16x32_bf16 v[92:95], v[132:135], v[206:209], v[92:95]
	v_mfma_f32_16x16x32_bf16 v[88:91], v[158:161], v[206:209], v[88:91]
	v_mfma_f32_16x16x32_bf16 v[76:79], v[132:135], v[214:217], v[76:79]
	v_mfma_f32_16x16x32_bf16 v[72:75], v[158:161], v[214:217], v[72:75]
	s_setprio 0
	s_setprio 1
	v_mfma_f32_16x16x32_bf16 v[116:119], v[162:165], v[186:189], v[116:119]
	v_mfma_f32_16x16x32_bf16 v[112:115], v[170:173], v[186:189], v[112:115]
	v_mfma_f32_16x16x32_bf16 v[100:103], v[162:165], v[194:197], v[100:103]
	v_mfma_f32_16x16x32_bf16 v[96:99], v[170:173], v[194:197], v[96:99]
	v_mfma_f32_16x16x32_bf16 v[84:87], v[162:165], v[202:205], v[84:87]
	v_mfma_f32_16x16x32_bf16 v[80:83], v[170:173], v[202:205], v[80:83]
	v_mfma_f32_16x16x32_bf16 v[68:71], v[162:165], v[210:213], v[68:71]
	v_mfma_f32_16x16x32_bf16 v[64:67], v[170:173], v[210:213], v[64:67]
	v_mfma_f32_16x16x32_bf16 v[116:119], v[166:169], v[190:193], v[116:119]
	v_mfma_f32_16x16x32_bf16 v[112:115], v[182:185], v[190:193], v[112:115]
	v_mfma_f32_16x16x32_bf16 v[100:103], v[166:169], v[198:201], v[100:103]
	v_mfma_f32_16x16x32_bf16 v[96:99], v[182:185], v[198:201], v[96:99]
	v_mfma_f32_16x16x32_bf16 v[84:87], v[166:169], v[206:209], v[84:87]
	v_mfma_f32_16x16x32_bf16 v[80:83], v[182:185], v[206:209], v[80:83]
	v_mfma_f32_16x16x32_bf16 v[68:71], v[166:169], v[214:217], v[68:71]
	v_mfma_f32_16x16x32_bf16 v[64:67], v[182:185], v[214:217], v[64:67]
	s_setprio 0
	s_barrier
	s_add_i32 s45, s79, s54
	v_lshl_add_u64 v[218:219], s[10:11], 0, v[138:139]
	s_mov_b32 m0, s45
	ds_read_b128 v[186:189], v177 offset:16384
	ds_read_b128 v[190:193], v177 offset:17408
	ds_read_b128 v[194:197], v177 offset:18432
	ds_read_b128 v[198:201], v177 offset:19456
	ds_read_b128 v[202:205], v177 offset:20480
	ds_read_b128 v[206:209], v177 offset:21504
	ds_read_b128 v[210:213], v177 offset:22528
	ds_read_b128 v[214:217], v177 offset:23552
	global_load_lds_dwordx4 v[218:219], off
	s_add_i32 m0, s45, 0x2000
	s_add_u32 s48, s10, 0x40000
	v_lshl_add_u64 v[220:221], s[10:11], 0, v[142:143]
	s_addc_u32 s49, s11, 0
	s_add_i32 s45, s80, s54
	global_load_lds_dwordx4 v[220:221], off
	v_lshl_add_u64 v[222:223], s[48:49], 0, v[138:139]
	s_mov_b32 m0, s45
	v_lshl_add_u64 v[224:225], s[12:13], 0, v[140:141]
	global_load_lds_dwordx4 v[222:223], off
	v_lshl_add_u64 v[222:223], s[48:49], 0, v[142:143]
	s_add_i32 m0, s45, 0x2000
	s_nop 0
	global_load_lds_dwordx4 v[222:223], off
	v_lshl_add_u64 v[222:223], s[12:13], 0, v[136:137]
	s_mov_b32 m0, s55
	s_nop 0
	global_load_lds_dwordx4 v[222:223], off
	s_mov_b32 m0, s56
	s_nop 0
	global_load_lds_dwordx4 v[224:225], off
	s_waitcnt vmcnt(8)
	s_waitcnt lgkmcnt(0)
	s_barrier
	s_setprio 1
	s_waitcnt lgkmcnt(0)
	v_mfma_f32_16x16x32_bf16 v[60:63], v[128:131], v[186:189], v[60:63]
	v_mfma_f32_16x16x32_bf16 v[56:59], v[154:157], v[186:189], v[56:59]
	v_mfma_f32_16x16x32_bf16 v[44:47], v[128:131], v[194:197], v[44:47]
	v_mfma_f32_16x16x32_bf16 v[40:43], v[154:157], v[194:197], v[40:43]
	v_mfma_f32_16x16x32_bf16 v[28:31], v[128:131], v[202:205], v[28:31]
	v_mfma_f32_16x16x32_bf16 v[24:27], v[154:157], v[202:205], v[24:27]
	v_mfma_f32_16x16x32_bf16 v[12:15], v[128:131], v[210:213], v[12:15]
	v_mfma_f32_16x16x32_bf16 v[8:11], v[154:157], v[210:213], v[8:11]
	v_mfma_f32_16x16x32_bf16 v[60:63], v[132:135], v[190:193], v[60:63]
	v_mfma_f32_16x16x32_bf16 v[56:59], v[158:161], v[190:193], v[56:59]
	v_mfma_f32_16x16x32_bf16 v[44:47], v[132:135], v[198:201], v[44:47]
	v_mfma_f32_16x16x32_bf16 v[40:43], v[158:161], v[198:201], v[40:43]
	v_mfma_f32_16x16x32_bf16 v[28:31], v[132:135], v[206:209], v[28:31]
	v_mfma_f32_16x16x32_bf16 v[24:27], v[158:161], v[206:209], v[24:27]
	v_mfma_f32_16x16x32_bf16 v[12:15], v[132:135], v[214:217], v[12:15]
	v_mfma_f32_16x16x32_bf16 v[8:11], v[158:161], v[214:217], v[8:11]
	s_setprio 0
	s_setprio 1
	v_mfma_f32_16x16x32_bf16 v[52:55], v[162:165], v[186:189], v[52:55]
	v_mfma_f32_16x16x32_bf16 v[48:51], v[170:173], v[186:189], v[48:51]
	v_mfma_f32_16x16x32_bf16 v[36:39], v[162:165], v[194:197], v[36:39]
	v_mfma_f32_16x16x32_bf16 v[32:35], v[170:173], v[194:197], v[32:35]
	v_mfma_f32_16x16x32_bf16 v[20:23], v[162:165], v[202:205], v[20:23]
	v_mfma_f32_16x16x32_bf16 v[16:19], v[170:173], v[202:205], v[16:19]
	v_mfma_f32_16x16x32_bf16 v[4:7], v[162:165], v[210:213], v[4:7]
	v_mfma_f32_16x16x32_bf16 v[0:3], v[170:173], v[210:213], v[0:3]
	v_mfma_f32_16x16x32_bf16 v[52:55], v[166:169], v[190:193], v[52:55]
	v_mfma_f32_16x16x32_bf16 v[48:51], v[182:185], v[190:193], v[48:51]
	v_mfma_f32_16x16x32_bf16 v[36:39], v[166:169], v[198:201], v[36:39]
	v_mfma_f32_16x16x32_bf16 v[32:35], v[182:185], v[198:201], v[32:35]
	v_mfma_f32_16x16x32_bf16 v[20:23], v[166:169], v[206:209], v[20:23]
	v_mfma_f32_16x16x32_bf16 v[16:19], v[182:185], v[206:209], v[16:19]
	v_mfma_f32_16x16x32_bf16 v[4:7], v[166:169], v[214:217], v[4:7]
	v_mfma_f32_16x16x32_bf16 v[0:3], v[182:185], v[214:217], v[0:3]
	s_setprio 0
	s_barrier
	s_add_i32 s45, 0, 0x18000
	v_add_u32_e32 v144, s45, v174
	s_add_i32 s48, 0, 0x1c000
	ds_read_b128 v[128:131], v144
	ds_read_b128 v[132:135], v144 offset:1024
	ds_read_b128 v[154:157], v144 offset:2048
	ds_read_b128 v[158:161], v144 offset:3072
	v_add_u32_e32 v144, s48, v174
	ds_read_b128 v[162:165], v144
	ds_read_b128 v[166:169], v144 offset:1024
	ds_read_b128 v[170:173], v144 offset:2048
	ds_read_b128 v[182:185], v144 offset:3072
	s_add_u32 s12, s12, 0x40000
	s_addc_u32 s13, s13, 0
	s_mov_b32 m0, s57
	v_lshl_add_u64 v[226:227], s[12:13], 0, v[136:137]
	ds_read_b128 v[186:189], v177 offset:32768
	ds_read_b128 v[190:193], v177 offset:33792
	ds_read_b128 v[194:197], v177 offset:34816
	ds_read_b128 v[198:201], v177 offset:35840
	ds_read_b128 v[202:205], v177 offset:36864
	ds_read_b128 v[206:209], v177 offset:37888
	ds_read_b128 v[210:213], v177 offset:38912
	ds_read_b128 v[214:217], v177 offset:39936
	global_load_lds_dwordx4 v[226:227], off
	v_lshl_add_u64 v[226:227], s[12:13], 0, v[140:141]
	s_mov_b32 m0, s58
	s_nop 0
	global_load_lds_dwordx4 v[226:227], off
	s_waitcnt vmcnt(8)
	s_waitcnt lgkmcnt(0)
	s_barrier
	s_setprio 1
	s_waitcnt lgkmcnt(0)
	v_mfma_f32_16x16x32_bf16 v[124:127], v[128:131], v[186:189], v[124:127]
	v_mfma_f32_16x16x32_bf16 v[120:123], v[154:157], v[186:189], v[120:123]
	v_mfma_f32_16x16x32_bf16 v[108:111], v[128:131], v[194:197], v[108:111]
	v_mfma_f32_16x16x32_bf16 v[104:107], v[154:157], v[194:197], v[104:107]
	v_mfma_f32_16x16x32_bf16 v[92:95], v[128:131], v[202:205], v[92:95]
	v_mfma_f32_16x16x32_bf16 v[88:91], v[154:157], v[202:205], v[88:91]
	v_mfma_f32_16x16x32_bf16 v[76:79], v[128:131], v[210:213], v[76:79]
	v_mfma_f32_16x16x32_bf16 v[72:75], v[154:157], v[210:213], v[72:75]
	v_mfma_f32_16x16x32_bf16 v[124:127], v[132:135], v[190:193], v[124:127]
	v_mfma_f32_16x16x32_bf16 v[120:123], v[158:161], v[190:193], v[120:123]
	v_mfma_f32_16x16x32_bf16 v[108:111], v[132:135], v[198:201], v[108:111]
	v_mfma_f32_16x16x32_bf16 v[104:107], v[158:161], v[198:201], v[104:107]
	v_mfma_f32_16x16x32_bf16 v[92:95], v[132:135], v[206:209], v[92:95]
	v_mfma_f32_16x16x32_bf16 v[88:91], v[158:161], v[206:209], v[88:91]
	v_mfma_f32_16x16x32_bf16 v[76:79], v[132:135], v[214:217], v[76:79]
	v_mfma_f32_16x16x32_bf16 v[72:75], v[158:161], v[214:217], v[72:75]
	s_setprio 0
	s_setprio 1
	v_mfma_f32_16x16x32_bf16 v[116:119], v[162:165], v[186:189], v[116:119]
	v_mfma_f32_16x16x32_bf16 v[112:115], v[170:173], v[186:189], v[112:115]
	v_mfma_f32_16x16x32_bf16 v[100:103], v[162:165], v[194:197], v[100:103]
	v_mfma_f32_16x16x32_bf16 v[96:99], v[170:173], v[194:197], v[96:99]
	v_mfma_f32_16x16x32_bf16 v[84:87], v[162:165], v[202:205], v[84:87]
	v_mfma_f32_16x16x32_bf16 v[80:83], v[170:173], v[202:205], v[80:83]
	v_mfma_f32_16x16x32_bf16 v[68:71], v[162:165], v[210:213], v[68:71]
	v_mfma_f32_16x16x32_bf16 v[64:67], v[170:173], v[210:213], v[64:67]
	v_mfma_f32_16x16x32_bf16 v[116:119], v[166:169], v[190:193], v[116:119]
	v_mfma_f32_16x16x32_bf16 v[112:115], v[182:185], v[190:193], v[112:115]
	v_mfma_f32_16x16x32_bf16 v[100:103], v[166:169], v[198:201], v[100:103]
	v_mfma_f32_16x16x32_bf16 v[96:99], v[182:185], v[198:201], v[96:99]
	v_mfma_f32_16x16x32_bf16 v[84:87], v[166:169], v[206:209], v[84:87]
	v_mfma_f32_16x16x32_bf16 v[80:83], v[182:185], v[206:209], v[80:83]
	v_mfma_f32_16x16x32_bf16 v[68:71], v[166:169], v[214:217], v[68:71]
	v_mfma_f32_16x16x32_bf16 v[64:67], v[182:185], v[214:217], v[64:67]
	s_setprio 0
	s_barrier
	s_add_i32 s12, s45, s54
	v_lshl_add_u64 v[218:219], v[218:219], 0, s[24:25]
	s_mov_b32 m0, s12
	ds_read_b128 v[186:189], v177 offset:49152
	ds_read_b128 v[190:193], v177 offset:50176
	ds_read_b128 v[194:197], v177 offset:51200
	ds_read_b128 v[198:201], v177 offset:52224
	ds_read_b128 v[202:205], v177 offset:53248
	ds_read_b128 v[206:209], v177 offset:54272
	ds_read_b128 v[210:213], v177 offset:55296
	ds_read_b128 v[214:217], v177 offset:56320
	global_load_lds_dwordx4 v[218:219], off
	s_add_i32 m0, s12, 0x2000
	s_add_u32 s10, s10, 0x40080
	v_lshl_add_u64 v[218:219], v[220:221], 0, s[24:25]
	s_addc_u32 s11, s11, 0
	s_add_i32 s12, s48, s54
	global_load_lds_dwordx4 v[218:219], off
	v_lshl_add_u64 v[218:219], s[10:11], 0, v[138:139]
	s_mov_b32 m0, s12
	s_nop 0
	global_load_lds_dwordx4 v[218:219], off
	v_lshl_add_u64 v[218:219], s[10:11], 0, v[142:143]
	s_add_i32 m0, s12, 0x2000
	s_nop 0
	global_load_lds_dwordx4 v[218:219], off
	v_lshl_add_u64 v[218:219], v[222:223], 0, s[24:25]
	s_mov_b32 m0, s77
	s_nop 0
	global_load_lds_dwordx4 v[218:219], off
	v_lshl_add_u64 v[218:219], v[224:225], 0, s[24:25]
	s_mov_b32 m0, s78
	s_nop 0
	global_load_lds_dwordx4 v[218:219], off
	s_waitcnt vmcnt(8)
	s_waitcnt lgkmcnt(0)
	s_barrier
	s_setprio 1
	s_waitcnt lgkmcnt(0)
	v_mfma_f32_16x16x32_bf16 v[60:63], v[128:131], v[186:189], v[60:63]
	v_mfma_f32_16x16x32_bf16 v[56:59], v[154:157], v[186:189], v[56:59]
	v_mfma_f32_16x16x32_bf16 v[44:47], v[128:131], v[194:197], v[44:47]
	v_mfma_f32_16x16x32_bf16 v[40:43], v[154:157], v[194:197], v[40:43]
	v_mfma_f32_16x16x32_bf16 v[28:31], v[128:131], v[202:205], v[28:31]
	v_mfma_f32_16x16x32_bf16 v[24:27], v[154:157], v[202:205], v[24:27]
	v_mfma_f32_16x16x32_bf16 v[12:15], v[128:131], v[210:213], v[12:15]
	v_mfma_f32_16x16x32_bf16 v[8:11], v[154:157], v[210:213], v[8:11]
	v_mfma_f32_16x16x32_bf16 v[60:63], v[132:135], v[190:193], v[60:63]
	v_mfma_f32_16x16x32_bf16 v[56:59], v[158:161], v[190:193], v[56:59]
	v_mfma_f32_16x16x32_bf16 v[44:47], v[132:135], v[198:201], v[44:47]
	v_mfma_f32_16x16x32_bf16 v[40:43], v[158:161], v[198:201], v[40:43]
	v_mfma_f32_16x16x32_bf16 v[28:31], v[132:135], v[206:209], v[28:31]
	v_mfma_f32_16x16x32_bf16 v[24:27], v[158:161], v[206:209], v[24:27]
	v_mfma_f32_16x16x32_bf16 v[12:15], v[132:135], v[214:217], v[12:15]
	v_mfma_f32_16x16x32_bf16 v[8:11], v[158:161], v[214:217], v[8:11]
	s_setprio 0
	s_setprio 1
	v_mfma_f32_16x16x32_bf16 v[52:55], v[162:165], v[186:189], v[52:55]
	v_mfma_f32_16x16x32_bf16 v[48:51], v[170:173], v[186:189], v[48:51]
	v_mfma_f32_16x16x32_bf16 v[36:39], v[162:165], v[194:197], v[36:39]
	v_mfma_f32_16x16x32_bf16 v[32:35], v[170:173], v[194:197], v[32:35]
	v_mfma_f32_16x16x32_bf16 v[20:23], v[162:165], v[202:205], v[20:23]
	v_mfma_f32_16x16x32_bf16 v[16:19], v[170:173], v[202:205], v[16:19]
	v_mfma_f32_16x16x32_bf16 v[4:7], v[162:165], v[210:213], v[4:7]
	v_mfma_f32_16x16x32_bf16 v[0:3], v[170:173], v[210:213], v[0:3]
	v_mfma_f32_16x16x32_bf16 v[52:55], v[166:169], v[190:193], v[52:55]
	v_mfma_f32_16x16x32_bf16 v[48:51], v[182:185], v[190:193], v[48:51]
	v_mfma_f32_16x16x32_bf16 v[36:39], v[166:169], v[198:201], v[36:39]
	v_mfma_f32_16x16x32_bf16 v[32:35], v[182:185], v[198:201], v[32:35]
	v_mfma_f32_16x16x32_bf16 v[20:23], v[166:169], v[206:209], v[20:23]
	v_mfma_f32_16x16x32_bf16 v[16:19], v[182:185], v[206:209], v[16:19]
	v_mfma_f32_16x16x32_bf16 v[4:7], v[166:169], v[214:217], v[4:7]
	v_mfma_f32_16x16x32_bf16 v[0:3], v[182:185], v[214:217], v[0:3]
	s_setprio 0
	s_add_i32 s44, s44, 2
	s_add_u32 s8, s8, 0x100
	s_addc_u32 s9, s9, 0
	s_add_u32 s42, s42, 0x100
	s_addc_u32 s43, s43, 0
	s_cmp_gt_u32 s44, 13
	s_barrier
	s_cbranch_scc0 .LBB0_1566
	s_and_b64 vcc, exec, s[26:27]
	s_cbranch_vccz .LBB0_1569
	s_barrier

.Lmm_11_7:
	s_setprio 0
	s_add_i32 s63, s63, 2
	s_add_u32 s34, s34, 0x100
	s_addc_u32 s35, s35, 0
	s_add_u32 s58, s58, 0x100
	s_addc_u32 s59, s59, 0
	s_cmp_gt_u32 s63, 13
	s_barrier
	s_cbranch_scc0 .Lqk_11
	s_branch .Lqk_join_11

.LBB0_1835:
	ds_read_b128 v[140:143], v182
	ds_read_b128 v[144:147], v182 offset:1024
	ds_read_b128 v[148:151], v182 offset:2048
	ds_read_b128 v[152:155], v182 offset:3072
	ds_read_b128 v[156:159], v183
	ds_read_b128 v[160:163], v183 offset:1024
	ds_read_b128 v[164:167], v183 offset:2048
	ds_read_b128 v[168:171], v183 offset:3072
	s_add_u32 s36, s34, 0xfffc0080
	s_addc_u32 s37, s35, -1
	s_cmp_eq_u32 s63, 12
	s_cselect_b32 s39, s23, s37
	s_cselect_b32 s38, s29, s36
	s_cselect_b32 s37, s21, s59
	s_cselect_b32 s36, s57, s58
	v_lshl_add_u64 v[210:211], s[34:35], 0, v[132:133]
	s_add_i32 m0, s31, 0xc000
	ds_read_b128 v[172:175], v184
	ds_read_b128 v[176:179], v184 offset:1024
	ds_read_b128 v[186:189], v184 offset:2048
	ds_read_b128 v[190:193], v184 offset:3072
	ds_read_b128 v[194:197], v184 offset:4096
	ds_read_b128 v[198:201], v184 offset:5120
	ds_read_b128 v[202:205], v184 offset:6144
	ds_read_b128 v[206:209], v184 offset:7168
	global_load_lds_dwordx4 v[210:211], off
	v_lshl_add_u64 v[210:211], s[34:35], 0, v[134:135]
	s_add_i32 m0, s31, 0xe000
	s_nop 0
	global_load_lds_dwordx4 v[210:211], off
	s_waitcnt vmcnt(8)
	s_waitcnt lgkmcnt(0)
	s_barrier
	s_setprio 1
	s_waitcnt lgkmcnt(0)
	v_mfma_f32_16x16x32_bf16 v[124:127], v[140:143], v[172:175], v[124:127]
	v_mfma_f32_16x16x32_bf16 v[120:123], v[148:151], v[172:175], v[120:123]
	v_mfma_f32_16x16x32_bf16 v[108:111], v[140:143], v[186:189], v[108:111]
	v_mfma_f32_16x16x32_bf16 v[104:107], v[148:151], v[186:189], v[104:107]
	v_mfma_f32_16x16x32_bf16 v[92:95], v[140:143], v[194:197], v[92:95]
	v_mfma_f32_16x16x32_bf16 v[88:91], v[148:151], v[194:197], v[88:91]
	v_mfma_f32_16x16x32_bf16 v[76:79], v[140:143], v[202:205], v[76:79]
	v_mfma_f32_16x16x32_bf16 v[72:75], v[148:151], v[202:205], v[72:75]
	v_mfma_f32_16x16x32_bf16 v[124:127], v[144:147], v[176:179], v[124:127]
	v_mfma_f32_16x16x32_bf16 v[120:123], v[152:155], v[176:179], v[120:123]
	v_mfma_f32_16x16x32_bf16 v[108:111], v[144:147], v[190:193], v[108:111]
	v_mfma_f32_16x16x32_bf16 v[104:107], v[152:155], v[190:193], v[104:107]
	v_mfma_f32_16x16x32_bf16 v[92:95], v[144:147], v[198:201], v[92:95]
	v_mfma_f32_16x16x32_bf16 v[88:91], v[152:155], v[198:201], v[88:91]
	v_mfma_f32_16x16x32_bf16 v[76:79], v[144:147], v[206:209], v[76:79]
	v_mfma_f32_16x16x32_bf16 v[72:75], v[152:155], v[206:209], v[72:75]
	s_setprio 0
	s_setprio 1
	v_mfma_f32_16x16x32_bf16 v[116:119], v[156:159], v[172:175], v[116:119]
	v_mfma_f32_16x16x32_bf16 v[112:115], v[164:167], v[172:175], v[112:115]
	v_mfma_f32_16x16x32_bf16 v[100:103], v[156:159], v[186:189], v[100:103]
	v_mfma_f32_16x16x32_bf16 v[96:99], v[164:167], v[186:189], v[96:99]
	v_mfma_f32_16x16x32_bf16 v[84:87], v[156:159], v[194:197], v[84:87]
	v_mfma_f32_16x16x32_bf16 v[80:83], v[164:167], v[194:197], v[80:83]
	v_mfma_f32_16x16x32_bf16 v[68:71], v[156:159], v[202:205], v[68:71]
	v_mfma_f32_16x16x32_bf16 v[64:67], v[164:167], v[202:205], v[64:67]
	v_mfma_f32_16x16x32_bf16 v[116:119], v[160:163], v[176:179], v[116:119]
	v_mfma_f32_16x16x32_bf16 v[112:115], v[168:171], v[176:179], v[112:115]
	v_mfma_f32_16x16x32_bf16 v[100:103], v[160:163], v[190:193], v[100:103]
	v_mfma_f32_16x16x32_bf16 v[96:99], v[168:171], v[190:193], v[96:99]
	v_mfma_f32_16x16x32_bf16 v[84:87], v[160:163], v[198:201], v[84:87]
	v_mfma_f32_16x16x32_bf16 v[80:83], v[168:171], v[198:201], v[80:83]
	v_mfma_f32_16x16x32_bf16 v[68:71], v[160:163], v[206:209], v[68:71]
	v_mfma_f32_16x16x32_bf16 v[64:67], v[168:171], v[206:209], v[64:67]
	s_setprio 0
	s_barrier
	s_add_i32 s64, s55, s44
	v_lshl_add_u64 v[210:211], s[36:37], 0, v[128:129]
	s_mov_b32 m0, s64
	ds_read_b128 v[172:175], v184 offset:16384
	ds_read_b128 v[176:179], v184 offset:17408
	ds_read_b128 v[186:189], v184 offset:18432
	ds_read_b128 v[190:193], v184 offset:19456
	ds_read_b128 v[194:197], v184 offset:20480
	ds_read_b128 v[198:201], v184 offset:21504
	ds_read_b128 v[202:205], v184 offset:22528
	ds_read_b128 v[206:209], v184 offset:23552
	global_load_lds_dwordx4 v[210:211], off
	s_add_i32 m0, s64, 0x2000
	s_add_u32 s64, s36, 0x40000
	v_lshl_add_u64 v[212:213], s[36:37], 0, v[130:131]
	s_addc_u32 s65, s37, 0
	s_add_i32 s66, s56, s44
	global_load_lds_dwordx4 v[212:213], off
	v_lshl_add_u64 v[214:215], s[64:65], 0, v[128:129]
	s_mov_b32 m0, s66
	v_lshl_add_u64 v[216:217], s[38:39], 0, v[130:131]
	global_load_lds_dwordx4 v[214:215], off
	v_lshl_add_u64 v[214:215], s[64:65], 0, v[130:131]
	s_add_i32 m0, s66, 0x2000
	s_nop 0
	global_load_lds_dwordx4 v[214:215], off
	v_lshl_add_u64 v[214:215], s[38:39], 0, v[128:129]
	s_mov_b32 m0, s31
	s_nop 0
	global_load_lds_dwordx4 v[214:215], off
	s_mov_b32 m0, s45
	s_nop 0
	global_load_lds_dwordx4 v[216:217], off
	s_waitcnt vmcnt(8)
	s_waitcnt lgkmcnt(0)
	s_barrier
	s_setprio 1
	s_waitcnt lgkmcnt(0)
	v_mfma_f32_16x16x32_bf16 v[60:63], v[140:143], v[172:175], v[60:63]
	v_mfma_f32_16x16x32_bf16 v[56:59], v[148:151], v[172:175], v[56:59]
	v_mfma_f32_16x16x32_bf16 v[44:47], v[140:143], v[186:189], v[44:47]
	v_mfma_f32_16x16x32_bf16 v[40:43], v[148:151], v[186:189], v[40:43]
	v_mfma_f32_16x16x32_bf16 v[28:31], v[140:143], v[194:197], v[28:31]
	v_mfma_f32_16x16x32_bf16 v[24:27], v[148:151], v[194:197], v[24:27]
	v_mfma_f32_16x16x32_bf16 v[12:15], v[140:143], v[202:205], v[12:15]
	v_mfma_f32_16x16x32_bf16 v[8:11], v[148:151], v[202:205], v[8:11]
	v_mfma_f32_16x16x32_bf16 v[60:63], v[144:147], v[176:179], v[60:63]
	v_mfma_f32_16x16x32_bf16 v[56:59], v[152:155], v[176:179], v[56:59]
	v_mfma_f32_16x16x32_bf16 v[44:47], v[144:147], v[190:193], v[44:47]
	v_mfma_f32_16x16x32_bf16 v[40:43], v[152:155], v[190:193], v[40:43]
	v_mfma_f32_16x16x32_bf16 v[28:31], v[144:147], v[198:201], v[28:31]
	v_mfma_f32_16x16x32_bf16 v[24:27], v[152:155], v[198:201], v[24:27]
	v_mfma_f32_16x16x32_bf16 v[12:15], v[144:147], v[206:209], v[12:15]
	v_mfma_f32_16x16x32_bf16 v[8:11], v[152:155], v[206:209], v[8:11]
	s_setprio 0
	s_setprio 1
	v_mfma_f32_16x16x32_bf16 v[52:55], v[156:159], v[172:175], v[52:55]
	v_mfma_f32_16x16x32_bf16 v[48:51], v[164:167], v[172:175], v[48:51]
	v_mfma_f32_16x16x32_bf16 v[36:39], v[156:159], v[186:189], v[36:39]
	v_mfma_f32_16x16x32_bf16 v[32:35], v[164:167], v[186:189], v[32:35]
	v_mfma_f32_16x16x32_bf16 v[20:23], v[156:159], v[194:197], v[20:23]
	v_mfma_f32_16x16x32_bf16 v[16:19], v[164:167], v[194:197], v[16:19]
	v_mfma_f32_16x16x32_bf16 v[4:7], v[156:159], v[202:205], v[4:7]
	v_mfma_f32_16x16x32_bf16 v[0:3], v[164:167], v[202:205], v[0:3]
	v_mfma_f32_16x16x32_bf16 v[52:55], v[160:163], v[176:179], v[52:55]
	v_mfma_f32_16x16x32_bf16 v[48:51], v[168:171], v[176:179], v[48:51]
	v_mfma_f32_16x16x32_bf16 v[36:39], v[160:163], v[190:193], v[36:39]
	v_mfma_f32_16x16x32_bf16 v[32:35], v[168:171], v[190:193], v[32:35]
	v_mfma_f32_16x16x32_bf16 v[20:23], v[160:163], v[198:201], v[20:23]
	v_mfma_f32_16x16x32_bf16 v[16:19], v[168:171], v[198:201], v[16:19]
	v_mfma_f32_16x16x32_bf16 v[4:7], v[160:163], v[206:209], v[4:7]
	v_mfma_f32_16x16x32_bf16 v[0:3], v[168:171], v[206:209], v[0:3]
	s_setprio 0
	s_barrier
	s_add_i32 s64, 0, 0x18000
	s_add_i32 s65, 0, 0x1c000
	v_add_u32_e32 v152, s64, v181
	v_add_u32_e32 v168, s65, v181
	ds_read_b128 v[140:143], v152
	ds_read_b128 v[144:147], v152 offset:1024
	ds_read_b128 v[148:151], v152 offset:2048
	ds_read_b128 v[152:155], v152 offset:3072
	ds_read_b128 v[156:159], v168
	ds_read_b128 v[160:163], v168 offset:1024
	ds_read_b128 v[164:167], v168 offset:2048
	ds_read_b128 v[168:171], v168 offset:3072
	s_add_u32 s38, s38, 0x40000
	s_addc_u32 s39, s39, 0
	s_mov_b32 m0, s48
	v_lshl_add_u64 v[218:219], s[38:39], 0, v[128:129]
	ds_read_b128 v[172:175], v184 offset:32768
	ds_read_b128 v[176:179], v184 offset:33792
	ds_read_b128 v[186:189], v184 offset:34816
	ds_read_b128 v[190:193], v184 offset:35840
	ds_read_b128 v[194:197], v184 offset:36864
	ds_read_b128 v[198:201], v184 offset:37888
	ds_read_b128 v[202:205], v184 offset:38912
	ds_read_b128 v[206:209], v184 offset:39936
	global_load_lds_dwordx4 v[218:219], off
	v_lshl_add_u64 v[218:219], s[38:39], 0, v[130:131]
	s_mov_b32 m0, s49
	s_nop 0
	global_load_lds_dwordx4 v[218:219], off
	s_waitcnt vmcnt(8)
	s_waitcnt lgkmcnt(0)
	s_barrier
	s_setprio 1
	s_waitcnt lgkmcnt(0)
	v_mfma_f32_16x16x32_bf16 v[124:127], v[140:143], v[172:175], v[124:127]
	v_mfma_f32_16x16x32_bf16 v[120:123], v[148:151], v[172:175], v[120:123]
	v_mfma_f32_16x16x32_bf16 v[108:111], v[140:143], v[186:189], v[108:111]
	v_mfma_f32_16x16x32_bf16 v[104:107], v[148:151], v[186:189], v[104:107]
	v_mfma_f32_16x16x32_bf16 v[92:95], v[140:143], v[194:197], v[92:95]
	v_mfma_f32_16x16x32_bf16 v[88:91], v[148:151], v[194:197], v[88:91]
	v_mfma_f32_16x16x32_bf16 v[76:79], v[140:143], v[202:205], v[76:79]
	v_mfma_f32_16x16x32_bf16 v[72:75], v[148:151], v[202:205], v[72:75]
	v_mfma_f32_16x16x32_bf16 v[124:127], v[144:147], v[176:179], v[124:127]
	v_mfma_f32_16x16x32_bf16 v[120:123], v[152:155], v[176:179], v[120:123]
	v_mfma_f32_16x16x32_bf16 v[108:111], v[144:147], v[190:193], v[108:111]
	v_mfma_f32_16x16x32_bf16 v[104:107], v[152:155], v[190:193], v[104:107]
	v_mfma_f32_16x16x32_bf16 v[92:95], v[144:147], v[198:201], v[92:95]
	v_mfma_f32_16x16x32_bf16 v[88:91], v[152:155], v[198:201], v[88:91]
	v_mfma_f32_16x16x32_bf16 v[76:79], v[144:147], v[206:209], v[76:79]
	v_mfma_f32_16x16x32_bf16 v[72:75], v[152:155], v[206:209], v[72:75]
	s_setprio 0
	s_setprio 1
	v_mfma_f32_16x16x32_bf16 v[116:119], v[156:159], v[172:175], v[116:119]
	v_mfma_f32_16x16x32_bf16 v[112:115], v[164:167], v[172:175], v[112:115]
	v_mfma_f32_16x16x32_bf16 v[100:103], v[156:159], v[186:189], v[100:103]
	v_mfma_f32_16x16x32_bf16 v[96:99], v[164:167], v[186:189], v[96:99]
	v_mfma_f32_16x16x32_bf16 v[84:87], v[156:159], v[194:197], v[84:87]
	v_mfma_f32_16x16x32_bf16 v[80:83], v[164:167], v[194:197], v[80:83]
	v_mfma_f32_16x16x32_bf16 v[68:71], v[156:159], v[202:205], v[68:71]
	v_mfma_f32_16x16x32_bf16 v[64:67], v[164:167], v[202:205], v[64:67]
	v_mfma_f32_16x16x32_bf16 v[116:119], v[160:163], v[176:179], v[116:119]
	v_mfma_f32_16x16x32_bf16 v[112:115], v[168:171], v[176:179], v[112:115]
	v_mfma_f32_16x16x32_bf16 v[100:103], v[160:163], v[190:193], v[100:103]
	v_mfma_f32_16x16x32_bf16 v[96:99], v[168:171], v[190:193], v[96:99]
	v_mfma_f32_16x16x32_bf16 v[84:87], v[160:163], v[198:201], v[84:87]
	v_mfma_f32_16x16x32_bf16 v[80:83], v[168:171], v[198:201], v[80:83]
	v_mfma_f32_16x16x32_bf16 v[68:71], v[160:163], v[206:209], v[68:71]
	v_mfma_f32_16x16x32_bf16 v[64:67], v[168:171], v[206:209], v[64:67]
	s_setprio 0
	s_barrier
	s_add_i32 s38, s64, s44
	v_lshl_add_u64 v[210:211], v[210:211], 0, s[14:15]
	s_mov_b32 m0, s38
	ds_read_b128 v[172:175], v184 offset:49152
	ds_read_b128 v[176:179], v184 offset:50176
	ds_read_b128 v[186:189], v184 offset:51200
	ds_read_b128 v[190:193], v184 offset:52224
	ds_read_b128 v[194:197], v184 offset:53248
	ds_read_b128 v[198:201], v184 offset:54272
	ds_read_b128 v[202:205], v184 offset:55296
	ds_read_b128 v[206:209], v184 offset:56320
	global_load_lds_dwordx4 v[210:211], off
	s_add_i32 m0, s38, 0x2000
	s_add_u32 s36, s36, 0x40080
	v_lshl_add_u64 v[210:211], v[212:213], 0, s[14:15]
	s_addc_u32 s37, s37, 0
	s_add_i32 s38, s65, s44
	global_load_lds_dwordx4 v[210:211], off
	v_lshl_add_u64 v[210:211], s[36:37], 0, v[128:129]
	s_mov_b32 m0, s38
	s_nop 0
	global_load_lds_dwordx4 v[210:211], off
	v_lshl_add_u64 v[210:211], s[36:37], 0, v[130:131]
	s_add_i32 m0, s38, 0x2000
	s_nop 0
	global_load_lds_dwordx4 v[210:211], off
	v_lshl_add_u64 v[210:211], v[214:215], 0, s[14:15]
	s_mov_b32 m0, s53
	s_nop 0
	global_load_lds_dwordx4 v[210:211], off
	v_lshl_add_u64 v[210:211], v[216:217], 0, s[14:15]
	s_mov_b32 m0, s54
	s_nop 0
	global_load_lds_dwordx4 v[210:211], off
	s_waitcnt vmcnt(8)
	s_waitcnt lgkmcnt(0)
	s_barrier
	s_setprio 1
	s_waitcnt lgkmcnt(0)
	v_mfma_f32_16x16x32_bf16 v[60:63], v[140:143], v[172:175], v[60:63]
	v_mfma_f32_16x16x32_bf16 v[56:59], v[148:151], v[172:175], v[56:59]
	v_mfma_f32_16x16x32_bf16 v[44:47], v[140:143], v[186:189], v[44:47]
	v_mfma_f32_16x16x32_bf16 v[40:43], v[148:151], v[186:189], v[40:43]
	v_mfma_f32_16x16x32_bf16 v[28:31], v[140:143], v[194:197], v[28:31]
	v_mfma_f32_16x16x32_bf16 v[24:27], v[148:151], v[194:197], v[24:27]
	v_mfma_f32_16x16x32_bf16 v[12:15], v[140:143], v[202:205], v[12:15]
	v_mfma_f32_16x16x32_bf16 v[8:11], v[148:151], v[202:205], v[8:11]
	v_mfma_f32_16x16x32_bf16 v[60:63], v[144:147], v[176:179], v[60:63]
	v_mfma_f32_16x16x32_bf16 v[56:59], v[152:155], v[176:179], v[56:59]
	v_mfma_f32_16x16x32_bf16 v[44:47], v[144:147], v[190:193], v[44:47]
	v_mfma_f32_16x16x32_bf16 v[40:43], v[152:155], v[190:193], v[40:43]
	v_mfma_f32_16x16x32_bf16 v[28:31], v[144:147], v[198:201], v[28:31]
	v_mfma_f32_16x16x32_bf16 v[24:27], v[152:155], v[198:201], v[24:27]
	v_mfma_f32_16x16x32_bf16 v[12:15], v[144:147], v[206:209], v[12:15]
	v_mfma_f32_16x16x32_bf16 v[8:11], v[152:155], v[206:209], v[8:11]
	s_setprio 0
	s_setprio 1
	v_mfma_f32_16x16x32_bf16 v[52:55], v[156:159], v[172:175], v[52:55]
	v_mfma_f32_16x16x32_bf16 v[48:51], v[164:167], v[172:175], v[48:51]
	v_mfma_f32_16x16x32_bf16 v[36:39], v[156:159], v[186:189], v[36:39]
	v_mfma_f32_16x16x32_bf16 v[32:35], v[164:167], v[186:189], v[32:35]
	v_mfma_f32_16x16x32_bf16 v[20:23], v[156:159], v[194:197], v[20:23]
	v_mfma_f32_16x16x32_bf16 v[16:19], v[164:167], v[194:197], v[16:19]
	v_mfma_f32_16x16x32_bf16 v[4:7], v[156:159], v[202:205], v[4:7]
	v_mfma_f32_16x16x32_bf16 v[0:3], v[164:167], v[202:205], v[0:3]
	v_mfma_f32_16x16x32_bf16 v[52:55], v[160:163], v[176:179], v[52:55]
	v_mfma_f32_16x16x32_bf16 v[48:51], v[168:171], v[176:179], v[48:51]
	v_mfma_f32_16x16x32_bf16 v[36:39], v[160:163], v[190:193], v[36:39]
	v_mfma_f32_16x16x32_bf16 v[32:35], v[168:171], v[190:193], v[32:35]
	v_mfma_f32_16x16x32_bf16 v[20:23], v[160:163], v[198:201], v[20:23]
	v_mfma_f32_16x16x32_bf16 v[16:19], v[168:171], v[198:201], v[16:19]
	v_mfma_f32_16x16x32_bf16 v[4:7], v[160:163], v[206:209], v[4:7]
	v_mfma_f32_16x16x32_bf16 v[0:3], v[168:171], v[206:209], v[0:3]
	s_setprio 0
	s_add_i32 s63, s63, 2
	s_add_u32 s34, s34, 0x100
	s_addc_u32 s35, s35, 0
	s_add_u32 s58, s58, 0x100
	s_addc_u32 s59, s59, 0
	s_cmp_gt_u32 s63, 13
	s_barrier
	s_cbranch_scc0 .LBB0_1835

.LBB0_1881:
	ds_read_b128 v[144:147], v155
	ds_read_b128 v[148:151], v155 offset:1024
	ds_read_b128 v[160:163], v155 offset:2048
	ds_read_b128 v[164:167], v155 offset:3072
	ds_read_b128 v[168:171], v156
	ds_read_b128 v[172:175], v156 offset:1024
	ds_read_b128 v[176:179], v156 offset:2048
	ds_read_b128 v[182:185], v156 offset:3072
	s_add_u32 s30, s28, 0xfffc0080
	s_addc_u32 s31, s29, -1
	s_cmp_eq_u32 s61, 12
	s_cselect_b32 s35, s23, s31
	s_cselect_b32 s34, s56, s30
	s_cselect_b32 s31, s21, s59
	s_cselect_b32 s30, s57, s58
	v_lshl_add_u64 v[152:153], s[28:29], 0, v[136:137]
	s_add_i32 m0, s41, 0xc000
	ds_read_b128 v[186:189], v157
	ds_read_b128 v[190:193], v157 offset:1024
	ds_read_b128 v[194:197], v157 offset:2048
	ds_read_b128 v[198:201], v157 offset:3072
	ds_read_b128 v[202:205], v157 offset:4096
	ds_read_b128 v[206:209], v157 offset:5120
	ds_read_b128 v[210:213], v157 offset:6144
	ds_read_b128 v[214:217], v157 offset:7168
	global_load_lds_dwordx4 v[152:153], off
	v_lshl_add_u64 v[152:153], s[28:29], 0, v[138:139]
	s_add_i32 m0, s41, 0xe000
	s_nop 0
	global_load_lds_dwordx4 v[152:153], off
	s_waitcnt vmcnt(8)
	s_waitcnt lgkmcnt(0)
	s_barrier
	s_setprio 1
	s_waitcnt lgkmcnt(0)
	v_mfma_f32_16x16x32_bf16 v[124:127], v[144:147], v[186:189], v[124:127]
	v_mfma_f32_16x16x32_bf16 v[120:123], v[160:163], v[186:189], v[120:123]
	v_mfma_f32_16x16x32_bf16 v[108:111], v[144:147], v[194:197], v[108:111]
	v_mfma_f32_16x16x32_bf16 v[104:107], v[160:163], v[194:197], v[104:107]
	v_mfma_f32_16x16x32_bf16 v[92:95], v[144:147], v[202:205], v[92:95]
	v_mfma_f32_16x16x32_bf16 v[88:91], v[160:163], v[202:205], v[88:91]
	v_mfma_f32_16x16x32_bf16 v[76:79], v[144:147], v[210:213], v[76:79]
	v_mfma_f32_16x16x32_bf16 v[72:75], v[160:163], v[210:213], v[72:75]
	v_mfma_f32_16x16x32_bf16 v[124:127], v[148:151], v[190:193], v[124:127]
	v_mfma_f32_16x16x32_bf16 v[120:123], v[164:167], v[190:193], v[120:123]
	v_mfma_f32_16x16x32_bf16 v[108:111], v[148:151], v[198:201], v[108:111]
	v_mfma_f32_16x16x32_bf16 v[104:107], v[164:167], v[198:201], v[104:107]
	v_mfma_f32_16x16x32_bf16 v[92:95], v[148:151], v[206:209], v[92:95]
	v_mfma_f32_16x16x32_bf16 v[88:91], v[164:167], v[206:209], v[88:91]
	v_mfma_f32_16x16x32_bf16 v[76:79], v[148:151], v[214:217], v[76:79]
	v_mfma_f32_16x16x32_bf16 v[72:75], v[164:167], v[214:217], v[72:75]
	s_setprio 0
	s_setprio 1
	v_mfma_f32_16x16x32_bf16 v[116:119], v[168:171], v[186:189], v[116:119]
	v_mfma_f32_16x16x32_bf16 v[112:115], v[176:179], v[186:189], v[112:115]
	v_mfma_f32_16x16x32_bf16 v[100:103], v[168:171], v[194:197], v[100:103]
	v_mfma_f32_16x16x32_bf16 v[96:99], v[176:179], v[194:197], v[96:99]
	v_mfma_f32_16x16x32_bf16 v[84:87], v[168:171], v[202:205], v[84:87]
	v_mfma_f32_16x16x32_bf16 v[80:83], v[176:179], v[202:205], v[80:83]
	v_mfma_f32_16x16x32_bf16 v[68:71], v[168:171], v[210:213], v[68:71]
	v_mfma_f32_16x16x32_bf16 v[64:67], v[176:179], v[210:213], v[64:67]
	v_mfma_f32_16x16x32_bf16 v[116:119], v[172:175], v[190:193], v[116:119]
	v_mfma_f32_16x16x32_bf16 v[112:115], v[182:185], v[190:193], v[112:115]
	v_mfma_f32_16x16x32_bf16 v[100:103], v[172:175], v[198:201], v[100:103]
	v_mfma_f32_16x16x32_bf16 v[96:99], v[182:185], v[198:201], v[96:99]
	v_mfma_f32_16x16x32_bf16 v[84:87], v[172:175], v[206:209], v[84:87]
	v_mfma_f32_16x16x32_bf16 v[80:83], v[182:185], v[206:209], v[80:83]
	v_mfma_f32_16x16x32_bf16 v[68:71], v[172:175], v[214:217], v[68:71]
	v_mfma_f32_16x16x32_bf16 v[64:67], v[182:185], v[214:217], v[64:67]
	s_setprio 0
	s_barrier
	s_add_i32 s62, s52, s40
	v_lshl_add_u64 v[152:153], s[30:31], 0, v[132:133]
	s_mov_b32 m0, s62
	ds_read_b128 v[186:189], v157 offset:16384
	ds_read_b128 v[190:193], v157 offset:17408
	ds_read_b128 v[194:197], v157 offset:18432
	ds_read_b128 v[198:201], v157 offset:19456
	ds_read_b128 v[202:205], v157 offset:20480
	ds_read_b128 v[206:209], v157 offset:21504
	ds_read_b128 v[210:213], v157 offset:22528
	ds_read_b128 v[214:217], v157 offset:23552
	global_load_lds_dwordx4 v[152:153], off
	s_add_i32 m0, s62, 0x2000
	s_add_u32 s62, s30, 0x40000
	v_lshl_add_u64 v[218:219], s[30:31], 0, v[128:129]
	s_addc_u32 s63, s31, 0
	s_add_i32 s64, s53, s40
	global_load_lds_dwordx4 v[218:219], off
	v_lshl_add_u64 v[220:221], s[62:63], 0, v[132:133]
	s_mov_b32 m0, s64
	v_lshl_add_u64 v[222:223], s[34:35], 0, v[130:131]
	global_load_lds_dwordx4 v[220:221], off
	v_lshl_add_u64 v[220:221], s[62:63], 0, v[128:129]
	s_add_i32 m0, s64, 0x2000
	s_nop 0
	global_load_lds_dwordx4 v[220:221], off
	v_lshl_add_u64 v[220:221], s[34:35], 0, v[134:135]
	s_mov_b32 m0, s41
	s_nop 0
	global_load_lds_dwordx4 v[220:221], off
	s_mov_b32 m0, s42
	s_nop 0
	global_load_lds_dwordx4 v[222:223], off
	s_waitcnt vmcnt(8)
	s_waitcnt lgkmcnt(0)
	s_barrier
	s_setprio 1
	s_waitcnt lgkmcnt(0)
	v_mfma_f32_16x16x32_bf16 v[60:63], v[144:147], v[186:189], v[60:63]
	v_mfma_f32_16x16x32_bf16 v[56:59], v[160:163], v[186:189], v[56:59]
	v_mfma_f32_16x16x32_bf16 v[44:47], v[144:147], v[194:197], v[44:47]
	v_mfma_f32_16x16x32_bf16 v[40:43], v[160:163], v[194:197], v[40:43]
	v_mfma_f32_16x16x32_bf16 v[28:31], v[144:147], v[202:205], v[28:31]
	v_mfma_f32_16x16x32_bf16 v[24:27], v[160:163], v[202:205], v[24:27]
	v_mfma_f32_16x16x32_bf16 v[12:15], v[144:147], v[210:213], v[12:15]
	v_mfma_f32_16x16x32_bf16 v[8:11], v[160:163], v[210:213], v[8:11]
	v_mfma_f32_16x16x32_bf16 v[60:63], v[148:151], v[190:193], v[60:63]
	v_mfma_f32_16x16x32_bf16 v[56:59], v[164:167], v[190:193], v[56:59]
	v_mfma_f32_16x16x32_bf16 v[44:47], v[148:151], v[198:201], v[44:47]
	v_mfma_f32_16x16x32_bf16 v[40:43], v[164:167], v[198:201], v[40:43]
	v_mfma_f32_16x16x32_bf16 v[28:31], v[148:151], v[206:209], v[28:31]
	v_mfma_f32_16x16x32_bf16 v[24:27], v[164:167], v[206:209], v[24:27]
	v_mfma_f32_16x16x32_bf16 v[12:15], v[148:151], v[214:217], v[12:15]
	v_mfma_f32_16x16x32_bf16 v[8:11], v[164:167], v[214:217], v[8:11]
	s_setprio 0
	s_setprio 1
	v_mfma_f32_16x16x32_bf16 v[52:55], v[168:171], v[186:189], v[52:55]
	v_mfma_f32_16x16x32_bf16 v[48:51], v[176:179], v[186:189], v[48:51]
	v_mfma_f32_16x16x32_bf16 v[36:39], v[168:171], v[194:197], v[36:39]
	v_mfma_f32_16x16x32_bf16 v[32:35], v[176:179], v[194:197], v[32:35]
	v_mfma_f32_16x16x32_bf16 v[20:23], v[168:171], v[202:205], v[20:23]
	v_mfma_f32_16x16x32_bf16 v[16:19], v[176:179], v[202:205], v[16:19]
	v_mfma_f32_16x16x32_bf16 v[4:7], v[168:171], v[210:213], v[4:7]
	v_mfma_f32_16x16x32_bf16 v[0:3], v[176:179], v[210:213], v[0:3]
	v_mfma_f32_16x16x32_bf16 v[52:55], v[172:175], v[190:193], v[52:55]
	v_mfma_f32_16x16x32_bf16 v[48:51], v[182:185], v[190:193], v[48:51]
	v_mfma_f32_16x16x32_bf16 v[36:39], v[172:175], v[198:201], v[36:39]
	v_mfma_f32_16x16x32_bf16 v[32:35], v[182:185], v[198:201], v[32:35]
	v_mfma_f32_16x16x32_bf16 v[20:23], v[172:175], v[206:209], v[20:23]
	v_mfma_f32_16x16x32_bf16 v[16:19], v[182:185], v[206:209], v[16:19]
	v_mfma_f32_16x16x32_bf16 v[4:7], v[172:175], v[214:217], v[4:7]
	v_mfma_f32_16x16x32_bf16 v[0:3], v[182:185], v[214:217], v[0:3]
	s_setprio 0
	s_barrier
	s_add_i32 s62, 0, 0x18000
	v_add_u32_e32 v159, s62, v154
	s_add_i32 s63, 0, 0x1c000
	ds_read_b128 v[144:147], v159
	ds_read_b128 v[148:151], v159 offset:1024
	ds_read_b128 v[160:163], v159 offset:2048
	ds_read_b128 v[164:167], v159 offset:3072
	v_add_u32_e32 v159, s63, v154
	ds_read_b128 v[168:171], v159
	ds_read_b128 v[172:175], v159 offset:1024
	ds_read_b128 v[176:179], v159 offset:2048
	ds_read_b128 v[182:185], v159 offset:3072
	s_add_u32 s34, s34, 0x40000
	s_addc_u32 s35, s35, 0
	s_mov_b32 m0, s43
	v_lshl_add_u64 v[224:225], s[34:35], 0, v[134:135]
	ds_read_b128 v[186:189], v157 offset:32768
	ds_read_b128 v[190:193], v157 offset:33792
	ds_read_b128 v[194:197], v157 offset:34816
	ds_read_b128 v[198:201], v157 offset:35840
	ds_read_b128 v[202:205], v157 offset:36864
	ds_read_b128 v[206:209], v157 offset:37888
	ds_read_b128 v[210:213], v157 offset:38912
	ds_read_b128 v[214:217], v157 offset:39936
	global_load_lds_dwordx4 v[224:225], off
	v_lshl_add_u64 v[224:225], s[34:35], 0, v[130:131]
	s_mov_b32 m0, s44
	s_nop 0
	global_load_lds_dwordx4 v[224:225], off
	s_waitcnt vmcnt(8)
	s_waitcnt lgkmcnt(0)
	s_barrier
	s_setprio 1
	s_waitcnt lgkmcnt(0)
	v_mfma_f32_16x16x32_bf16 v[124:127], v[144:147], v[186:189], v[124:127]
	v_mfma_f32_16x16x32_bf16 v[120:123], v[160:163], v[186:189], v[120:123]
	v_mfma_f32_16x16x32_bf16 v[108:111], v[144:147], v[194:197], v[108:111]
	v_mfma_f32_16x16x32_bf16 v[104:107], v[160:163], v[194:197], v[104:107]
	v_mfma_f32_16x16x32_bf16 v[92:95], v[144:147], v[202:205], v[92:95]
	v_mfma_f32_16x16x32_bf16 v[88:91], v[160:163], v[202:205], v[88:91]
	v_mfma_f32_16x16x32_bf16 v[76:79], v[144:147], v[210:213], v[76:79]
	v_mfma_f32_16x16x32_bf16 v[72:75], v[160:163], v[210:213], v[72:75]
	v_mfma_f32_16x16x32_bf16 v[124:127], v[148:151], v[190:193], v[124:127]
	v_mfma_f32_16x16x32_bf16 v[120:123], v[164:167], v[190:193], v[120:123]
	v_mfma_f32_16x16x32_bf16 v[108:111], v[148:151], v[198:201], v[108:111]
	v_mfma_f32_16x16x32_bf16 v[104:107], v[164:167], v[198:201], v[104:107]
	v_mfma_f32_16x16x32_bf16 v[92:95], v[148:151], v[206:209], v[92:95]
	v_mfma_f32_16x16x32_bf16 v[88:91], v[164:167], v[206:209], v[88:91]
	v_mfma_f32_16x16x32_bf16 v[76:79], v[148:151], v[214:217], v[76:79]
	v_mfma_f32_16x16x32_bf16 v[72:75], v[164:167], v[214:217], v[72:75]
	s_setprio 0
	s_setprio 1
	v_mfma_f32_16x16x32_bf16 v[116:119], v[168:171], v[186:189], v[116:119]
	v_mfma_f32_16x16x32_bf16 v[112:115], v[176:179], v[186:189], v[112:115]
	v_mfma_f32_16x16x32_bf16 v[100:103], v[168:171], v[194:197], v[100:103]
	v_mfma_f32_16x16x32_bf16 v[96:99], v[176:179], v[194:197], v[96:99]
	v_mfma_f32_16x16x32_bf16 v[84:87], v[168:171], v[202:205], v[84:87]
	v_mfma_f32_16x16x32_bf16 v[80:83], v[176:179], v[202:205], v[80:83]
	v_mfma_f32_16x16x32_bf16 v[68:71], v[168:171], v[210:213], v[68:71]
	v_mfma_f32_16x16x32_bf16 v[64:67], v[176:179], v[210:213], v[64:67]
	v_mfma_f32_16x16x32_bf16 v[116:119], v[172:175], v[190:193], v[116:119]
	v_mfma_f32_16x16x32_bf16 v[112:115], v[182:185], v[190:193], v[112:115]
	v_mfma_f32_16x16x32_bf16 v[100:103], v[172:175], v[198:201], v[100:103]
	v_mfma_f32_16x16x32_bf16 v[96:99], v[182:185], v[198:201], v[96:99]
	v_mfma_f32_16x16x32_bf16 v[84:87], v[172:175], v[206:209], v[84:87]
	v_mfma_f32_16x16x32_bf16 v[80:83], v[182:185], v[206:209], v[80:83]
	v_mfma_f32_16x16x32_bf16 v[68:71], v[172:175], v[214:217], v[68:71]
	v_mfma_f32_16x16x32_bf16 v[64:67], v[182:185], v[214:217], v[64:67]
	s_setprio 0
	s_barrier
	s_add_i32 s34, s62, s40
	v_lshl_add_u64 v[152:153], v[152:153], 0, s[16:17]
	s_mov_b32 m0, s34
	ds_read_b128 v[186:189], v157 offset:49152
	ds_read_b128 v[190:193], v157 offset:50176
	ds_read_b128 v[194:197], v157 offset:51200
	ds_read_b128 v[198:201], v157 offset:52224
	ds_read_b128 v[202:205], v157 offset:53248
	ds_read_b128 v[206:209], v157 offset:54272
	ds_read_b128 v[210:213], v157 offset:55296
	ds_read_b128 v[214:217], v157 offset:56320
	global_load_lds_dwordx4 v[152:153], off
	s_add_i32 m0, s34, 0x2000
	s_add_u32 s30, s30, 0x40080
	v_lshl_add_u64 v[152:153], v[218:219], 0, s[16:17]
	s_addc_u32 s31, s31, 0
	s_add_i32 s34, s63, s40
	global_load_lds_dwordx4 v[152:153], off
	v_lshl_add_u64 v[152:153], s[30:31], 0, v[132:133]
	s_mov_b32 m0, s34
	s_nop 0
	global_load_lds_dwordx4 v[152:153], off
	v_lshl_add_u64 v[152:153], s[30:31], 0, v[128:129]
	s_add_i32 m0, s34, 0x2000
	s_nop 0
	global_load_lds_dwordx4 v[152:153], off
	v_lshl_add_u64 v[152:153], v[220:221], 0, s[16:17]
	s_mov_b32 m0, s50
	s_nop 0
	global_load_lds_dwordx4 v[152:153], off
	v_lshl_add_u64 v[152:153], v[222:223], 0, s[16:17]
	s_mov_b32 m0, s51
	s_nop 0
	global_load_lds_dwordx4 v[152:153], off
	s_waitcnt vmcnt(8)
	s_waitcnt lgkmcnt(0)
	s_barrier
	s_setprio 1
	s_waitcnt lgkmcnt(0)
	v_mfma_f32_16x16x32_bf16 v[60:63], v[144:147], v[186:189], v[60:63]
	v_mfma_f32_16x16x32_bf16 v[56:59], v[160:163], v[186:189], v[56:59]
	v_mfma_f32_16x16x32_bf16 v[44:47], v[144:147], v[194:197], v[44:47]
	v_mfma_f32_16x16x32_bf16 v[40:43], v[160:163], v[194:197], v[40:43]
	v_mfma_f32_16x16x32_bf16 v[28:31], v[144:147], v[202:205], v[28:31]
	v_mfma_f32_16x16x32_bf16 v[24:27], v[160:163], v[202:205], v[24:27]
	v_mfma_f32_16x16x32_bf16 v[12:15], v[144:147], v[210:213], v[12:15]
	v_mfma_f32_16x16x32_bf16 v[8:11], v[160:163], v[210:213], v[8:11]
	v_mfma_f32_16x16x32_bf16 v[60:63], v[148:151], v[190:193], v[60:63]
	v_mfma_f32_16x16x32_bf16 v[56:59], v[164:167], v[190:193], v[56:59]
	v_mfma_f32_16x16x32_bf16 v[44:47], v[148:151], v[198:201], v[44:47]
	v_mfma_f32_16x16x32_bf16 v[40:43], v[164:167], v[198:201], v[40:43]
	v_mfma_f32_16x16x32_bf16 v[28:31], v[148:151], v[206:209], v[28:31]
	v_mfma_f32_16x16x32_bf16 v[24:27], v[164:167], v[206:209], v[24:27]
	v_mfma_f32_16x16x32_bf16 v[12:15], v[148:151], v[214:217], v[12:15]
	v_mfma_f32_16x16x32_bf16 v[8:11], v[164:167], v[214:217], v[8:11]
	s_setprio 0
	s_setprio 1
	v_mfma_f32_16x16x32_bf16 v[52:55], v[168:171], v[186:189], v[52:55]
	v_mfma_f32_16x16x32_bf16 v[48:51], v[176:179], v[186:189], v[48:51]
	v_mfma_f32_16x16x32_bf16 v[36:39], v[168:171], v[194:197], v[36:39]
	v_mfma_f32_16x16x32_bf16 v[32:35], v[176:179], v[194:197], v[32:35]
	v_mfma_f32_16x16x32_bf16 v[20:23], v[168:171], v[202:205], v[20:23]
	v_mfma_f32_16x16x32_bf16 v[16:19], v[176:179], v[202:205], v[16:19]
	v_mfma_f32_16x16x32_bf16 v[4:7], v[168:171], v[210:213], v[4:7]
	v_mfma_f32_16x16x32_bf16 v[0:3], v[176:179], v[210:213], v[0:3]
	v_mfma_f32_16x16x32_bf16 v[52:55], v[172:175], v[190:193], v[52:55]
	v_mfma_f32_16x16x32_bf16 v[48:51], v[182:185], v[190:193], v[48:51]
	v_mfma_f32_16x16x32_bf16 v[36:39], v[172:175], v[198:201], v[36:39]
	v_mfma_f32_16x16x32_bf16 v[32:35], v[182:185], v[198:201], v[32:35]
	v_mfma_f32_16x16x32_bf16 v[20:23], v[172:175], v[206:209], v[20:23]
	v_mfma_f32_16x16x32_bf16 v[16:19], v[182:185], v[206:209], v[16:19]
	v_mfma_f32_16x16x32_bf16 v[4:7], v[172:175], v[214:217], v[4:7]
	v_mfma_f32_16x16x32_bf16 v[0:3], v[182:185], v[214:217], v[0:3]
	s_setprio 0
	s_add_i32 s61, s61, 2
	s_add_u32 s28, s28, 0x100
	s_addc_u32 s29, s29, 0
	s_add_u32 s58, s58, 0x100
	s_addc_u32 s59, s59, 0
	s_cmp_gt_u32 s61, 13
	s_barrier
	s_cbranch_scc0 .LBB0_1881
	s_and_b64 vcc, exec, s[18:19]
	s_cbranch_vccz .LBB0_1884
	s_barrier

.Lmm_13_7:
	s_setprio 0
	s_add_i32 s51, s51, 2
	s_add_u32 s49, s49, 0x100
	s_addc_u32 s50, s50, 0
	s_cmp_gt_u32 s51, 41
	s_mov_b64 s[18:19], s[20:21]
	s_barrier
	s_cbranch_scc0 .Lqk_13
	s_branch .Lqk_join_13

.LBB0_1917:
	ds_read_b128 v[140:143], v182
	ds_read_b128 v[144:147], v182 offset:1024
	ds_read_b128 v[148:151], v182 offset:2048
	ds_read_b128 v[152:155], v182 offset:3072
	ds_read_b128 v[156:159], v183
	ds_read_b128 v[160:163], v183 offset:1024
	ds_read_b128 v[164:167], v183 offset:2048
	ds_read_b128 v[168:171], v183 offset:3072
	s_add_u32 s20, s18, 0x100
	s_addc_u32 s21, s19, 0
	s_cmp_eq_u32 s51, 40
	s_cselect_b32 s25, s7, s21
	s_cselect_b32 s24, s6, s20
	s_cselect_b32 s23, s17, s50
	s_cselect_b32 s22, s16, s49
	v_lshl_add_u64 v[210:211], s[18:19], 0, v[132:133]
	s_add_i32 m0, s31, 0xc000
	ds_read_b128 v[172:175], v184
	ds_read_b128 v[176:179], v184 offset:1024
	ds_read_b128 v[186:189], v184 offset:2048
	ds_read_b128 v[190:193], v184 offset:3072
	ds_read_b128 v[194:197], v184 offset:4096
	ds_read_b128 v[198:201], v184 offset:5120
	ds_read_b128 v[202:205], v184 offset:6144
	ds_read_b128 v[206:209], v184 offset:7168
	global_load_lds_dwordx4 v[210:211], off
	v_lshl_add_u64 v[210:211], s[18:19], 0, v[134:135]
	s_add_i32 m0, s31, 0xe000
	s_nop 0
	global_load_lds_dwordx4 v[210:211], off
	s_waitcnt vmcnt(8)
	s_waitcnt lgkmcnt(0)
	s_barrier
	s_setprio 1
	s_waitcnt lgkmcnt(0)
	v_mfma_f32_16x16x32_bf16 v[124:127], v[140:143], v[172:175], v[124:127]
	v_mfma_f32_16x16x32_bf16 v[120:123], v[148:151], v[172:175], v[120:123]
	v_mfma_f32_16x16x32_bf16 v[108:111], v[140:143], v[186:189], v[108:111]
	v_mfma_f32_16x16x32_bf16 v[104:107], v[148:151], v[186:189], v[104:107]
	v_mfma_f32_16x16x32_bf16 v[92:95], v[140:143], v[194:197], v[92:95]
	v_mfma_f32_16x16x32_bf16 v[88:91], v[148:151], v[194:197], v[88:91]
	v_mfma_f32_16x16x32_bf16 v[76:79], v[140:143], v[202:205], v[76:79]
	v_mfma_f32_16x16x32_bf16 v[72:75], v[148:151], v[202:205], v[72:75]
	v_mfma_f32_16x16x32_bf16 v[124:127], v[144:147], v[176:179], v[124:127]
	v_mfma_f32_16x16x32_bf16 v[120:123], v[152:155], v[176:179], v[120:123]
	v_mfma_f32_16x16x32_bf16 v[108:111], v[144:147], v[190:193], v[108:111]
	v_mfma_f32_16x16x32_bf16 v[104:107], v[152:155], v[190:193], v[104:107]
	v_mfma_f32_16x16x32_bf16 v[92:95], v[144:147], v[198:201], v[92:95]
	v_mfma_f32_16x16x32_bf16 v[88:91], v[152:155], v[198:201], v[88:91]
	v_mfma_f32_16x16x32_bf16 v[76:79], v[144:147], v[206:209], v[76:79]
	v_mfma_f32_16x16x32_bf16 v[72:75], v[152:155], v[206:209], v[72:75]
	s_setprio 0
	s_setprio 1
	v_mfma_f32_16x16x32_bf16 v[116:119], v[156:159], v[172:175], v[116:119]
	v_mfma_f32_16x16x32_bf16 v[112:115], v[164:167], v[172:175], v[112:115]
	v_mfma_f32_16x16x32_bf16 v[100:103], v[156:159], v[186:189], v[100:103]
	v_mfma_f32_16x16x32_bf16 v[96:99], v[164:167], v[186:189], v[96:99]
	v_mfma_f32_16x16x32_bf16 v[84:87], v[156:159], v[194:197], v[84:87]
	v_mfma_f32_16x16x32_bf16 v[80:83], v[164:167], v[194:197], v[80:83]
	v_mfma_f32_16x16x32_bf16 v[68:71], v[156:159], v[202:205], v[68:71]
	v_mfma_f32_16x16x32_bf16 v[64:67], v[164:167], v[202:205], v[64:67]
	v_mfma_f32_16x16x32_bf16 v[116:119], v[160:163], v[176:179], v[116:119]
	v_mfma_f32_16x16x32_bf16 v[112:115], v[168:171], v[176:179], v[112:115]
	v_mfma_f32_16x16x32_bf16 v[100:103], v[160:163], v[190:193], v[100:103]
	v_mfma_f32_16x16x32_bf16 v[96:99], v[168:171], v[190:193], v[96:99]
	v_mfma_f32_16x16x32_bf16 v[84:87], v[160:163], v[198:201], v[84:87]
	v_mfma_f32_16x16x32_bf16 v[80:83], v[168:171], v[198:201], v[80:83]
	v_mfma_f32_16x16x32_bf16 v[68:71], v[160:163], v[206:209], v[68:71]
	v_mfma_f32_16x16x32_bf16 v[64:67], v[168:171], v[206:209], v[64:67]
	s_setprio 0
	s_barrier
	s_add_i32 s18, s41, s30
	v_lshl_add_u64 v[210:211], s[22:23], 0, v[128:129]
	s_mov_b32 m0, s18
	ds_read_b128 v[172:175], v184 offset:16384
	ds_read_b128 v[176:179], v184 offset:17408
	ds_read_b128 v[186:189], v184 offset:18432
	ds_read_b128 v[190:193], v184 offset:19456
	ds_read_b128 v[194:197], v184 offset:20480
	ds_read_b128 v[198:201], v184 offset:21504
	ds_read_b128 v[202:205], v184 offset:22528
	ds_read_b128 v[206:209], v184 offset:23552
	global_load_lds_dwordx4 v[210:211], off
	s_add_i32 m0, s18, 0x2000
	s_add_u32 s18, s22, 0xb0000
	v_lshl_add_u64 v[212:213], s[22:23], 0, v[130:131]
	s_addc_u32 s19, s23, 0
	s_add_i32 s52, s42, s30
	global_load_lds_dwordx4 v[212:213], off
	v_lshl_add_u64 v[214:215], s[18:19], 0, v[128:129]
	s_mov_b32 m0, s52
	v_lshl_add_u64 v[216:217], s[24:25], 0, v[130:131]
	global_load_lds_dwordx4 v[214:215], off
	v_lshl_add_u64 v[214:215], s[18:19], 0, v[130:131]
	s_add_i32 m0, s52, 0x2000
	s_nop 0
	global_load_lds_dwordx4 v[214:215], off
	v_lshl_add_u64 v[214:215], s[24:25], 0, v[128:129]
	s_mov_b32 m0, s31
	s_nop 0
	global_load_lds_dwordx4 v[214:215], off
	s_mov_b32 m0, s33
	s_nop 0
	global_load_lds_dwordx4 v[216:217], off
	s_waitcnt vmcnt(8)
	s_waitcnt lgkmcnt(0)
	s_barrier
	s_setprio 1
	s_waitcnt lgkmcnt(0)
	v_mfma_f32_16x16x32_bf16 v[60:63], v[140:143], v[172:175], v[60:63]
	v_mfma_f32_16x16x32_bf16 v[56:59], v[148:151], v[172:175], v[56:59]
	v_mfma_f32_16x16x32_bf16 v[44:47], v[140:143], v[186:189], v[44:47]
	v_mfma_f32_16x16x32_bf16 v[40:43], v[148:151], v[186:189], v[40:43]
	v_mfma_f32_16x16x32_bf16 v[28:31], v[140:143], v[194:197], v[28:31]
	v_mfma_f32_16x16x32_bf16 v[24:27], v[148:151], v[194:197], v[24:27]
	v_mfma_f32_16x16x32_bf16 v[12:15], v[140:143], v[202:205], v[12:15]
	v_mfma_f32_16x16x32_bf16 v[8:11], v[148:151], v[202:205], v[8:11]
	v_mfma_f32_16x16x32_bf16 v[60:63], v[144:147], v[176:179], v[60:63]
	v_mfma_f32_16x16x32_bf16 v[56:59], v[152:155], v[176:179], v[56:59]
	v_mfma_f32_16x16x32_bf16 v[44:47], v[144:147], v[190:193], v[44:47]
	v_mfma_f32_16x16x32_bf16 v[40:43], v[152:155], v[190:193], v[40:43]
	v_mfma_f32_16x16x32_bf16 v[28:31], v[144:147], v[198:201], v[28:31]
	v_mfma_f32_16x16x32_bf16 v[24:27], v[152:155], v[198:201], v[24:27]
	v_mfma_f32_16x16x32_bf16 v[12:15], v[144:147], v[206:209], v[12:15]
	v_mfma_f32_16x16x32_bf16 v[8:11], v[152:155], v[206:209], v[8:11]
	s_setprio 0
	s_setprio 1
	v_mfma_f32_16x16x32_bf16 v[52:55], v[156:159], v[172:175], v[52:55]
	v_mfma_f32_16x16x32_bf16 v[48:51], v[164:167], v[172:175], v[48:51]
	v_mfma_f32_16x16x32_bf16 v[36:39], v[156:159], v[186:189], v[36:39]
	v_mfma_f32_16x16x32_bf16 v[32:35], v[164:167], v[186:189], v[32:35]
	v_mfma_f32_16x16x32_bf16 v[20:23], v[156:159], v[194:197], v[20:23]
	v_mfma_f32_16x16x32_bf16 v[16:19], v[164:167], v[194:197], v[16:19]
	v_mfma_f32_16x16x32_bf16 v[4:7], v[156:159], v[202:205], v[4:7]
	v_mfma_f32_16x16x32_bf16 v[0:3], v[164:167], v[202:205], v[0:3]
	v_mfma_f32_16x16x32_bf16 v[52:55], v[160:163], v[176:179], v[52:55]
	v_mfma_f32_16x16x32_bf16 v[48:51], v[168:171], v[176:179], v[48:51]
	v_mfma_f32_16x16x32_bf16 v[36:39], v[160:163], v[190:193], v[36:39]
	v_mfma_f32_16x16x32_bf16 v[32:35], v[168:171], v[190:193], v[32:35]
	v_mfma_f32_16x16x32_bf16 v[20:23], v[160:163], v[198:201], v[20:23]
	v_mfma_f32_16x16x32_bf16 v[16:19], v[168:171], v[198:201], v[16:19]
	v_mfma_f32_16x16x32_bf16 v[4:7], v[160:163], v[206:209], v[4:7]
	v_mfma_f32_16x16x32_bf16 v[0:3], v[168:171], v[206:209], v[0:3]
	s_setprio 0
	s_barrier
	s_add_i32 s52, 0, 0x18000
	s_add_i32 s53, 0, 0x1c000
	v_add_u32_e32 v152, s52, v181
	v_add_u32_e32 v168, s53, v181
	ds_read_b128 v[140:143], v152
	ds_read_b128 v[144:147], v152 offset:1024
	ds_read_b128 v[148:151], v152 offset:2048
	ds_read_b128 v[152:155], v152 offset:3072
	ds_read_b128 v[156:159], v168
	ds_read_b128 v[160:163], v168 offset:1024
	ds_read_b128 v[164:167], v168 offset:2048
	ds_read_b128 v[168:171], v168 offset:3072
	s_add_u32 s18, s24, 0xb0000
	s_addc_u32 s19, s25, 0
	s_mov_b32 m0, s34
	v_lshl_add_u64 v[218:219], s[18:19], 0, v[128:129]
	ds_read_b128 v[172:175], v184 offset:32768
	ds_read_b128 v[176:179], v184 offset:33792
	ds_read_b128 v[186:189], v184 offset:34816
	ds_read_b128 v[190:193], v184 offset:35840
	ds_read_b128 v[194:197], v184 offset:36864
	ds_read_b128 v[198:201], v184 offset:37888
	ds_read_b128 v[202:205], v184 offset:38912
	ds_read_b128 v[206:209], v184 offset:39936
	global_load_lds_dwordx4 v[218:219], off
	v_lshl_add_u64 v[218:219], s[18:19], 0, v[130:131]
	s_mov_b32 m0, s35
	s_nop 0
	global_load_lds_dwordx4 v[218:219], off
	s_waitcnt vmcnt(8)
	s_waitcnt lgkmcnt(0)
	s_barrier
	s_setprio 1
	s_waitcnt lgkmcnt(0)
	v_mfma_f32_16x16x32_bf16 v[124:127], v[140:143], v[172:175], v[124:127]
	v_mfma_f32_16x16x32_bf16 v[120:123], v[148:151], v[172:175], v[120:123]
	v_mfma_f32_16x16x32_bf16 v[108:111], v[140:143], v[186:189], v[108:111]
	v_mfma_f32_16x16x32_bf16 v[104:107], v[148:151], v[186:189], v[104:107]
	v_mfma_f32_16x16x32_bf16 v[92:95], v[140:143], v[194:197], v[92:95]
	v_mfma_f32_16x16x32_bf16 v[88:91], v[148:151], v[194:197], v[88:91]
	v_mfma_f32_16x16x32_bf16 v[76:79], v[140:143], v[202:205], v[76:79]
	v_mfma_f32_16x16x32_bf16 v[72:75], v[148:151], v[202:205], v[72:75]
	v_mfma_f32_16x16x32_bf16 v[124:127], v[144:147], v[176:179], v[124:127]
	v_mfma_f32_16x16x32_bf16 v[120:123], v[152:155], v[176:179], v[120:123]
	v_mfma_f32_16x16x32_bf16 v[108:111], v[144:147], v[190:193], v[108:111]
	v_mfma_f32_16x16x32_bf16 v[104:107], v[152:155], v[190:193], v[104:107]
	v_mfma_f32_16x16x32_bf16 v[92:95], v[144:147], v[198:201], v[92:95]
	v_mfma_f32_16x16x32_bf16 v[88:91], v[152:155], v[198:201], v[88:91]
	v_mfma_f32_16x16x32_bf16 v[76:79], v[144:147], v[206:209], v[76:79]
	v_mfma_f32_16x16x32_bf16 v[72:75], v[152:155], v[206:209], v[72:75]
	s_setprio 0
	s_setprio 1
	v_mfma_f32_16x16x32_bf16 v[116:119], v[156:159], v[172:175], v[116:119]
	v_mfma_f32_16x16x32_bf16 v[112:115], v[164:167], v[172:175], v[112:115]
	v_mfma_f32_16x16x32_bf16 v[100:103], v[156:159], v[186:189], v[100:103]
	v_mfma_f32_16x16x32_bf16 v[96:99], v[164:167], v[186:189], v[96:99]
	v_mfma_f32_16x16x32_bf16 v[84:87], v[156:159], v[194:197], v[84:87]
	v_mfma_f32_16x16x32_bf16 v[80:83], v[164:167], v[194:197], v[80:83]
	v_mfma_f32_16x16x32_bf16 v[68:71], v[156:159], v[202:205], v[68:71]
	v_mfma_f32_16x16x32_bf16 v[64:67], v[164:167], v[202:205], v[64:67]
	v_mfma_f32_16x16x32_bf16 v[116:119], v[160:163], v[176:179], v[116:119]
	v_mfma_f32_16x16x32_bf16 v[112:115], v[168:171], v[176:179], v[112:115]
	v_mfma_f32_16x16x32_bf16 v[100:103], v[160:163], v[190:193], v[100:103]
	v_mfma_f32_16x16x32_bf16 v[96:99], v[168:171], v[190:193], v[96:99]
	v_mfma_f32_16x16x32_bf16 v[84:87], v[160:163], v[198:201], v[84:87]
	v_mfma_f32_16x16x32_bf16 v[80:83], v[168:171], v[198:201], v[80:83]
	v_mfma_f32_16x16x32_bf16 v[68:71], v[160:163], v[206:209], v[68:71]
	v_mfma_f32_16x16x32_bf16 v[64:67], v[168:171], v[206:209], v[64:67]
	s_setprio 0
	s_barrier
	s_add_i32 s18, s52, s30
	v_lshl_add_u64 v[210:211], v[210:211], 0, s[12:13]
	s_mov_b32 m0, s18
	ds_read_b128 v[172:175], v184 offset:49152
	ds_read_b128 v[176:179], v184 offset:50176
	ds_read_b128 v[186:189], v184 offset:51200
	ds_read_b128 v[190:193], v184 offset:52224
	ds_read_b128 v[194:197], v184 offset:53248
	ds_read_b128 v[198:201], v184 offset:54272
	ds_read_b128 v[202:205], v184 offset:55296
	ds_read_b128 v[206:209], v184 offset:56320
	global_load_lds_dwordx4 v[210:211], off
	s_add_i32 m0, s18, 0x2000
	s_add_u32 s18, s22, 0xb0080
	v_lshl_add_u64 v[210:211], v[212:213], 0, s[12:13]
	s_addc_u32 s19, s23, 0
	s_add_i32 s22, s53, s30
	global_load_lds_dwordx4 v[210:211], off
	v_lshl_add_u64 v[210:211], s[18:19], 0, v[128:129]
	s_mov_b32 m0, s22
	s_nop 0
	global_load_lds_dwordx4 v[210:211], off
	v_lshl_add_u64 v[210:211], s[18:19], 0, v[130:131]
	s_add_i32 m0, s22, 0x2000
	s_nop 0
	global_load_lds_dwordx4 v[210:211], off
	v_lshl_add_u64 v[210:211], v[214:215], 0, s[12:13]
	s_mov_b32 m0, s39
	s_nop 0
	global_load_lds_dwordx4 v[210:211], off
	v_lshl_add_u64 v[210:211], v[216:217], 0, s[12:13]
	s_mov_b32 m0, s40
	s_nop 0
	global_load_lds_dwordx4 v[210:211], off
	s_waitcnt vmcnt(8)
	s_waitcnt lgkmcnt(0)
	s_barrier
	s_setprio 1
	s_waitcnt lgkmcnt(0)
	v_mfma_f32_16x16x32_bf16 v[60:63], v[140:143], v[172:175], v[60:63]
	v_mfma_f32_16x16x32_bf16 v[56:59], v[148:151], v[172:175], v[56:59]
	v_mfma_f32_16x16x32_bf16 v[44:47], v[140:143], v[186:189], v[44:47]
	v_mfma_f32_16x16x32_bf16 v[40:43], v[148:151], v[186:189], v[40:43]
	v_mfma_f32_16x16x32_bf16 v[28:31], v[140:143], v[194:197], v[28:31]
	v_mfma_f32_16x16x32_bf16 v[24:27], v[148:151], v[194:197], v[24:27]
	v_mfma_f32_16x16x32_bf16 v[12:15], v[140:143], v[202:205], v[12:15]
	v_mfma_f32_16x16x32_bf16 v[8:11], v[148:151], v[202:205], v[8:11]
	v_mfma_f32_16x16x32_bf16 v[60:63], v[144:147], v[176:179], v[60:63]
	v_mfma_f32_16x16x32_bf16 v[56:59], v[152:155], v[176:179], v[56:59]
	v_mfma_f32_16x16x32_bf16 v[44:47], v[144:147], v[190:193], v[44:47]
	v_mfma_f32_16x16x32_bf16 v[40:43], v[152:155], v[190:193], v[40:43]
	v_mfma_f32_16x16x32_bf16 v[28:31], v[144:147], v[198:201], v[28:31]
	v_mfma_f32_16x16x32_bf16 v[24:27], v[152:155], v[198:201], v[24:27]
	v_mfma_f32_16x16x32_bf16 v[12:15], v[144:147], v[206:209], v[12:15]
	v_mfma_f32_16x16x32_bf16 v[8:11], v[152:155], v[206:209], v[8:11]
	s_setprio 0
	s_setprio 1
	v_mfma_f32_16x16x32_bf16 v[52:55], v[156:159], v[172:175], v[52:55]
	v_mfma_f32_16x16x32_bf16 v[48:51], v[164:167], v[172:175], v[48:51]
	v_mfma_f32_16x16x32_bf16 v[36:39], v[156:159], v[186:189], v[36:39]
	v_mfma_f32_16x16x32_bf16 v[32:35], v[164:167], v[186:189], v[32:35]
	v_mfma_f32_16x16x32_bf16 v[20:23], v[156:159], v[194:197], v[20:23]
	v_mfma_f32_16x16x32_bf16 v[16:19], v[164:167], v[194:197], v[16:19]
	v_mfma_f32_16x16x32_bf16 v[4:7], v[156:159], v[202:205], v[4:7]
	v_mfma_f32_16x16x32_bf16 v[0:3], v[164:167], v[202:205], v[0:3]
	v_mfma_f32_16x16x32_bf16 v[52:55], v[160:163], v[176:179], v[52:55]
	v_mfma_f32_16x16x32_bf16 v[48:51], v[168:171], v[176:179], v[48:51]
	v_mfma_f32_16x16x32_bf16 v[36:39], v[160:163], v[190:193], v[36:39]
	v_mfma_f32_16x16x32_bf16 v[32:35], v[168:171], v[190:193], v[32:35]
	v_mfma_f32_16x16x32_bf16 v[20:23], v[160:163], v[198:201], v[20:23]
	v_mfma_f32_16x16x32_bf16 v[16:19], v[168:171], v[198:201], v[16:19]
	v_mfma_f32_16x16x32_bf16 v[4:7], v[160:163], v[206:209], v[4:7]
	v_mfma_f32_16x16x32_bf16 v[0:3], v[168:171], v[206:209], v[0:3]
	s_setprio 0
	s_add_i32 s51, s51, 2
	s_add_u32 s49, s49, 0x100
	s_addc_u32 s50, s50, 0
	s_cmp_gt_u32 s51, 41
	s_mov_b64 s[18:19], s[20:21]
	s_barrier
	s_cbranch_scc0 .LBB0_1917
